# v36 + GEMM K-loops: LDS-DMA loads use saddr form (SGPR base + 32-bit VGPR offset), removing 16 64-bit VALU address adds per iteration per wave
# speedup vs baseline: 1.0232x; 1.0017x over previous
.LBB0_261:
	s_add_u32 s0, s76, 0xfff80080
	s_addc_u32 s1, s77, -1
	s_and_b64 s[84:85], s[84:85], exec
	s_cselect_b32 vcc_hi, s22, s1
	s_cselect_b32 vcc_lo, s23, s0
	s_cselect_b32 s85, s49, s58
	s_cselect_b32 s84, s57, s51
	s_add_i32 s0, 0, 0x10000
	s_add_i32 s1, 0, 0x14000
	v_add_u32_e32 v158, s0, v176
	v_add_u32_e32 v174, s1, v176
	ds_read_b128 v[146:149], v158
	ds_read_b128 v[150:153], v158 offset:1024
	ds_read_b128 v[154:157], v158 offset:2048
	ds_read_b128 v[158:161], v158 offset:3072
	ds_read_b128 v[162:165], v174
	ds_read_b128 v[166:169], v174 offset:1024
	ds_read_b128 v[170:173], v174 offset:2048
	ds_read_b128 v[178:181], v174 offset:3072
	s_add_i32 m0, s21, 0xc000
	ds_read_b128 v[182:185], v177
	ds_read_b128 v[186:189], v177 offset:1024
	ds_read_b128 v[190:193], v177 offset:2048
	ds_read_b128 v[204:207], v177 offset:3072
	ds_read_b128 v[208:211], v177 offset:4096
	ds_read_b128 v[212:215], v177 offset:5120
	ds_read_b128 v[216:219], v177 offset:6144
	ds_read_b128 v[220:223], v177 offset:7168
	global_load_lds_dwordx4 v138, s[76:77]
	s_add_i32 m0, s21, 0xe000
	s_nop 0
	global_load_lds_dwordx4 v140, s[76:77]
	s_waitcnt vmcnt(8)
	s_waitcnt lgkmcnt(0)
	s_barrier
	s_setprio 1
	s_waitcnt lgkmcnt(0)
	v_mfma_f32_16x16x32_bf16 v[126:129], v[146:149], v[182:185], v[126:129]
	v_mfma_f32_16x16x32_bf16 v[126:129], v[150:153], v[186:189], v[126:129]
	v_mfma_f32_16x16x32_bf16 v[122:125], v[158:161], v[186:189], v[122:125]
	v_mfma_f32_16x16x32_bf16 v[122:125], v[154:157], v[182:185], v[122:125]
	v_mfma_f32_16x16x32_bf16 v[118:121], v[162:165], v[182:185], v[118:121]
	v_mfma_f32_16x16x32_bf16 v[118:121], v[166:169], v[186:189], v[118:121]
	v_mfma_f32_16x16x32_bf16 v[114:117], v[178:181], v[186:189], v[114:117]
	v_mfma_f32_16x16x32_bf16 v[114:117], v[170:173], v[182:185], v[114:117]
	v_mfma_f32_16x16x32_bf16 v[98:101], v[170:173], v[190:193], v[98:101]
	v_mfma_f32_16x16x32_bf16 v[98:101], v[178:181], v[204:207], v[98:101]
	v_mfma_f32_16x16x32_bf16 v[102:105], v[166:169], v[204:207], v[102:105]
	v_mfma_f32_16x16x32_bf16 v[102:105], v[162:165], v[190:193], v[102:105]
	v_mfma_f32_16x16x32_bf16 v[106:109], v[154:157], v[190:193], v[106:109]
	v_mfma_f32_16x16x32_bf16 v[106:109], v[158:161], v[204:207], v[106:109]
	v_mfma_f32_16x16x32_bf16 v[110:113], v[150:153], v[204:207], v[110:113]
	v_mfma_f32_16x16x32_bf16 v[110:113], v[146:149], v[190:193], v[110:113]
	v_mfma_f32_16x16x32_bf16 v[94:97], v[146:149], v[208:211], v[94:97]
	v_mfma_f32_16x16x32_bf16 v[94:97], v[150:153], v[212:215], v[94:97]
	v_mfma_f32_16x16x32_bf16 v[90:93], v[158:161], v[212:215], v[90:93]
	v_mfma_f32_16x16x32_bf16 v[90:93], v[154:157], v[208:211], v[90:93]
	v_mfma_f32_16x16x32_bf16 v[86:89], v[162:165], v[208:211], v[86:89]
	v_mfma_f32_16x16x32_bf16 v[86:89], v[166:169], v[212:215], v[86:89]
	v_mfma_f32_16x16x32_bf16 v[82:85], v[178:181], v[212:215], v[82:85]
	v_mfma_f32_16x16x32_bf16 v[82:85], v[170:173], v[208:211], v[82:85]
	v_mfma_f32_16x16x32_bf16 v[66:69], v[170:173], v[216:219], v[66:69]
	v_mfma_f32_16x16x32_bf16 v[66:69], v[178:181], v[220:223], v[66:69]
	v_mfma_f32_16x16x32_bf16 v[70:73], v[166:169], v[220:223], v[70:73]
	v_mfma_f32_16x16x32_bf16 v[70:73], v[162:165], v[216:219], v[70:73]
	v_mfma_f32_16x16x32_bf16 v[74:77], v[154:157], v[216:219], v[74:77]
	v_mfma_f32_16x16x32_bf16 v[74:77], v[158:161], v[220:223], v[74:77]
	v_mfma_f32_16x16x32_bf16 v[78:81], v[150:153], v[220:223], v[78:81]
	v_mfma_f32_16x16x32_bf16 v[78:81], v[146:149], v[216:219], v[78:81]
	s_setprio 0
	s_barrier
	s_add_i32 s0, s0, s20
	s_mov_b32 m0, s0
	ds_read_b128 v[182:185], v177 offset:16384
	ds_read_b128 v[186:189], v177 offset:17408
	ds_read_b128 v[190:193], v177 offset:18432
	ds_read_b128 v[204:207], v177 offset:19456
	ds_read_b128 v[208:211], v177 offset:20480
	ds_read_b128 v[212:215], v177 offset:21504
	ds_read_b128 v[216:219], v177 offset:22528
	ds_read_b128 v[220:223], v177 offset:23552
	global_load_lds_dwordx4 v132, s[84:85]
	s_add_i32 m0, s0, 0x2000
	s_add_u32 s94, s84, 0x80000
	s_addc_u32 s95, s85, 0
	s_add_i32 s0, s1, s20
	global_load_lds_dwordx4 v130, s[84:85]
	s_mov_b32 m0, s0
	s_nop 0
	global_load_lds_dwordx4 v132, s[94:95]
	s_add_i32 m0, s0, 0x2000
	s_nop 0
	global_load_lds_dwordx4 v130, s[94:95]
	s_mov_b32 m0, s21
	s_nop 0
	global_load_lds_dwordx4 v132, vcc
	s_mov_b32 m0, s26
	s_nop 0
	global_load_lds_dwordx4 v130, vcc
	s_waitcnt vmcnt(8)
	s_waitcnt lgkmcnt(0)
	s_barrier
	s_setprio 1
	s_waitcnt lgkmcnt(0)
	v_mfma_f32_16x16x32_bf16 v[62:65], v[146:149], v[182:185], v[62:65]
	v_mfma_f32_16x16x32_bf16 v[62:65], v[150:153], v[186:189], v[62:65]
	v_mfma_f32_16x16x32_bf16 v[58:61], v[158:161], v[186:189], v[58:61]
	v_mfma_f32_16x16x32_bf16 v[58:61], v[154:157], v[182:185], v[58:61]
	v_mfma_f32_16x16x32_bf16 v[54:57], v[162:165], v[182:185], v[54:57]
	v_mfma_f32_16x16x32_bf16 v[54:57], v[166:169], v[186:189], v[54:57]
	v_mfma_f32_16x16x32_bf16 v[50:53], v[178:181], v[186:189], v[50:53]
	v_mfma_f32_16x16x32_bf16 v[50:53], v[170:173], v[182:185], v[50:53]
	v_mfma_f32_16x16x32_bf16 v[34:37], v[170:173], v[190:193], v[34:37]
	v_mfma_f32_16x16x32_bf16 v[34:37], v[178:181], v[204:207], v[34:37]
	v_mfma_f32_16x16x32_bf16 v[38:41], v[166:169], v[204:207], v[38:41]
	v_mfma_f32_16x16x32_bf16 v[38:41], v[162:165], v[190:193], v[38:41]
	v_mfma_f32_16x16x32_bf16 v[42:45], v[154:157], v[190:193], v[42:45]
	v_mfma_f32_16x16x32_bf16 v[42:45], v[158:161], v[204:207], v[42:45]
	v_mfma_f32_16x16x32_bf16 v[46:49], v[150:153], v[204:207], v[46:49]
	v_mfma_f32_16x16x32_bf16 v[46:49], v[146:149], v[190:193], v[46:49]
	v_mfma_f32_16x16x32_bf16 v[30:33], v[146:149], v[208:211], v[30:33]
	v_mfma_f32_16x16x32_bf16 v[30:33], v[150:153], v[212:215], v[30:33]
	v_mfma_f32_16x16x32_bf16 v[26:29], v[158:161], v[212:215], v[26:29]
	v_mfma_f32_16x16x32_bf16 v[26:29], v[154:157], v[208:211], v[26:29]
	v_mfma_f32_16x16x32_bf16 v[22:25], v[162:165], v[208:211], v[22:25]
	v_mfma_f32_16x16x32_bf16 v[22:25], v[166:169], v[212:215], v[22:25]
	v_mfma_f32_16x16x32_bf16 v[18:21], v[178:181], v[212:215], v[18:21]
	v_mfma_f32_16x16x32_bf16 v[18:21], v[170:173], v[208:211], v[18:21]
	v_mfma_f32_16x16x32_bf16 v[2:5], v[170:173], v[216:219], v[2:5]
	v_mfma_f32_16x16x32_bf16 v[2:5], v[178:181], v[220:223], v[2:5]
	v_mfma_f32_16x16x32_bf16 v[6:9], v[166:169], v[220:223], v[6:9]
	v_mfma_f32_16x16x32_bf16 v[6:9], v[162:165], v[216:219], v[6:9]
	v_mfma_f32_16x16x32_bf16 v[10:13], v[154:157], v[216:219], v[10:13]
	v_mfma_f32_16x16x32_bf16 v[10:13], v[158:161], v[220:223], v[10:13]
	v_mfma_f32_16x16x32_bf16 v[14:17], v[150:153], v[220:223], v[14:17]
	v_mfma_f32_16x16x32_bf16 v[14:17], v[146:149], v[216:219], v[14:17]
	s_setprio 0
	s_barrier
	s_add_i32 s0, 0, 0x18000
	s_add_i32 s1, 0, 0x1c000
	v_add_u32_e32 v158, s0, v176
	v_add_u32_e32 v178, s1, v176
	ds_read_b128 v[146:149], v158
	ds_read_b128 v[150:153], v158 offset:1024
	ds_read_b128 v[154:157], v158 offset:2048
	ds_read_b128 v[158:161], v158 offset:3072
	ds_read_b128 v[162:165], v178
	ds_read_b128 v[166:169], v178 offset:1024
	ds_read_b128 v[170:173], v178 offset:2048
	ds_read_b128 v[178:181], v178 offset:3072
	s_add_u32 s94, vcc_lo, 0x80000
	s_addc_u32 s95, vcc_hi, 0
	s_mov_b32 m0, s27
	ds_read_b128 v[182:185], v177 offset:32768
	ds_read_b128 v[186:189], v177 offset:33792
	ds_read_b128 v[190:193], v177 offset:34816
	ds_read_b128 v[204:207], v177 offset:35840
	ds_read_b128 v[208:211], v177 offset:36864
	ds_read_b128 v[212:215], v177 offset:37888
	ds_read_b128 v[216:219], v177 offset:38912
	ds_read_b128 v[220:223], v177 offset:39936
	global_load_lds_dwordx4 v132, s[94:95]
	s_mov_b32 m0, s29
	s_nop 0
	global_load_lds_dwordx4 v130, s[94:95]
	s_waitcnt vmcnt(8)
	s_waitcnt lgkmcnt(0)
	s_barrier
	s_setprio 1
	s_waitcnt lgkmcnt(0)
	v_mfma_f32_16x16x32_bf16 v[126:129], v[146:149], v[182:185], v[126:129]
	v_mfma_f32_16x16x32_bf16 v[126:129], v[150:153], v[186:189], v[126:129]
	v_mfma_f32_16x16x32_bf16 v[122:125], v[158:161], v[186:189], v[122:125]
	v_mfma_f32_16x16x32_bf16 v[122:125], v[154:157], v[182:185], v[122:125]
	v_mfma_f32_16x16x32_bf16 v[118:121], v[162:165], v[182:185], v[118:121]
	v_mfma_f32_16x16x32_bf16 v[118:121], v[166:169], v[186:189], v[118:121]
	v_mfma_f32_16x16x32_bf16 v[114:117], v[178:181], v[186:189], v[114:117]
	v_mfma_f32_16x16x32_bf16 v[114:117], v[170:173], v[182:185], v[114:117]
	v_mfma_f32_16x16x32_bf16 v[98:101], v[170:173], v[190:193], v[98:101]
	v_mfma_f32_16x16x32_bf16 v[98:101], v[178:181], v[204:207], v[98:101]
	v_mfma_f32_16x16x32_bf16 v[102:105], v[166:169], v[204:207], v[102:105]
	v_mfma_f32_16x16x32_bf16 v[102:105], v[162:165], v[190:193], v[102:105]
	v_mfma_f32_16x16x32_bf16 v[106:109], v[154:157], v[190:193], v[106:109]
	v_mfma_f32_16x16x32_bf16 v[106:109], v[158:161], v[204:207], v[106:109]
	v_mfma_f32_16x16x32_bf16 v[110:113], v[150:153], v[204:207], v[110:113]
	v_mfma_f32_16x16x32_bf16 v[110:113], v[146:149], v[190:193], v[110:113]
	v_mfma_f32_16x16x32_bf16 v[94:97], v[146:149], v[208:211], v[94:97]
	v_mfma_f32_16x16x32_bf16 v[94:97], v[150:153], v[212:215], v[94:97]
	v_mfma_f32_16x16x32_bf16 v[90:93], v[158:161], v[212:215], v[90:93]
	v_mfma_f32_16x16x32_bf16 v[90:93], v[154:157], v[208:211], v[90:93]
	v_mfma_f32_16x16x32_bf16 v[86:89], v[162:165], v[208:211], v[86:89]
	v_mfma_f32_16x16x32_bf16 v[86:89], v[166:169], v[212:215], v[86:89]
	v_mfma_f32_16x16x32_bf16 v[82:85], v[178:181], v[212:215], v[82:85]
	v_mfma_f32_16x16x32_bf16 v[82:85], v[170:173], v[208:211], v[82:85]
	v_mfma_f32_16x16x32_bf16 v[66:69], v[170:173], v[216:219], v[66:69]
	v_mfma_f32_16x16x32_bf16 v[66:69], v[178:181], v[220:223], v[66:69]
	v_mfma_f32_16x16x32_bf16 v[70:73], v[166:169], v[220:223], v[70:73]
	v_mfma_f32_16x16x32_bf16 v[70:73], v[162:165], v[216:219], v[70:73]
	v_mfma_f32_16x16x32_bf16 v[74:77], v[154:157], v[216:219], v[74:77]
	v_mfma_f32_16x16x32_bf16 v[74:77], v[158:161], v[220:223], v[74:77]
	v_mfma_f32_16x16x32_bf16 v[78:81], v[150:153], v[220:223], v[78:81]
	v_mfma_f32_16x16x32_bf16 v[78:81], v[146:149], v[216:219], v[78:81]
	s_setprio 0
	s_barrier
	s_add_u32 s98, s84, 0x80
	s_addc_u32 s99, s85, 0
	s_add_u32 s100, vcc_lo, 0x80
	s_addc_u32 s101, vcc_hi, 0
	s_add_i32 s0, s0, s20
	s_mov_b32 m0, s0
	ds_read_b128 v[182:185], v177 offset:49152
	ds_read_b128 v[186:189], v177 offset:50176
	ds_read_b128 v[190:193], v177 offset:51200
	ds_read_b128 v[204:207], v177 offset:52224
	ds_read_b128 v[208:211], v177 offset:53248
	ds_read_b128 v[212:215], v177 offset:54272
	ds_read_b128 v[216:219], v177 offset:55296
	ds_read_b128 v[220:223], v177 offset:56320
	global_load_lds_dwordx4 v132, s[98:99]
	s_add_i32 m0, s0, 0x2000
	s_add_u32 s84, s84, 0x80080
	s_addc_u32 s85, s85, 0
	s_add_i32 s0, s1, s20
	global_load_lds_dwordx4 v130, s[98:99]
	s_mov_b32 m0, s0
	s_nop 0
	global_load_lds_dwordx4 v132, s[84:85]
	s_add_i32 m0, s0, 0x2000
	s_nop 0
	global_load_lds_dwordx4 v130, s[84:85]
	s_mov_b32 m0, s40
	s_nop 0
	global_load_lds_dwordx4 v132, s[100:101]
	s_mov_b32 m0, s41
	s_nop 0
	global_load_lds_dwordx4 v130, s[100:101]
	s_waitcnt vmcnt(8)
	s_waitcnt lgkmcnt(0)
	s_barrier
	s_setprio 1
	s_waitcnt lgkmcnt(0)
	v_mfma_f32_16x16x32_bf16 v[62:65], v[146:149], v[182:185], v[62:65]
	v_mfma_f32_16x16x32_bf16 v[62:65], v[150:153], v[186:189], v[62:65]
	v_mfma_f32_16x16x32_bf16 v[58:61], v[158:161], v[186:189], v[58:61]
	v_mfma_f32_16x16x32_bf16 v[58:61], v[154:157], v[182:185], v[58:61]
	v_mfma_f32_16x16x32_bf16 v[54:57], v[162:165], v[182:185], v[54:57]
	v_mfma_f32_16x16x32_bf16 v[54:57], v[166:169], v[186:189], v[54:57]
	v_mfma_f32_16x16x32_bf16 v[50:53], v[178:181], v[186:189], v[50:53]
	v_mfma_f32_16x16x32_bf16 v[50:53], v[170:173], v[182:185], v[50:53]
	v_mfma_f32_16x16x32_bf16 v[34:37], v[170:173], v[190:193], v[34:37]
	v_mfma_f32_16x16x32_bf16 v[34:37], v[178:181], v[204:207], v[34:37]
	v_mfma_f32_16x16x32_bf16 v[38:41], v[166:169], v[204:207], v[38:41]
	v_mfma_f32_16x16x32_bf16 v[38:41], v[162:165], v[190:193], v[38:41]
	v_mfma_f32_16x16x32_bf16 v[42:45], v[154:157], v[190:193], v[42:45]
	v_mfma_f32_16x16x32_bf16 v[42:45], v[158:161], v[204:207], v[42:45]
	v_mfma_f32_16x16x32_bf16 v[46:49], v[150:153], v[204:207], v[46:49]
	v_mfma_f32_16x16x32_bf16 v[46:49], v[146:149], v[190:193], v[46:49]
	v_mfma_f32_16x16x32_bf16 v[30:33], v[146:149], v[208:211], v[30:33]
	v_mfma_f32_16x16x32_bf16 v[30:33], v[150:153], v[212:215], v[30:33]
	v_mfma_f32_16x16x32_bf16 v[26:29], v[158:161], v[212:215], v[26:29]
	v_mfma_f32_16x16x32_bf16 v[26:29], v[154:157], v[208:211], v[26:29]
	v_mfma_f32_16x16x32_bf16 v[22:25], v[162:165], v[208:211], v[22:25]
	v_mfma_f32_16x16x32_bf16 v[22:25], v[166:169], v[212:215], v[22:25]
	v_mfma_f32_16x16x32_bf16 v[18:21], v[178:181], v[212:215], v[18:21]
	v_mfma_f32_16x16x32_bf16 v[18:21], v[170:173], v[208:211], v[18:21]
	v_mfma_f32_16x16x32_bf16 v[2:5], v[170:173], v[216:219], v[2:5]
	v_mfma_f32_16x16x32_bf16 v[2:5], v[178:181], v[220:223], v[2:5]
	v_mfma_f32_16x16x32_bf16 v[6:9], v[166:169], v[220:223], v[6:9]
	v_mfma_f32_16x16x32_bf16 v[6:9], v[162:165], v[216:219], v[6:9]
	v_mfma_f32_16x16x32_bf16 v[10:13], v[154:157], v[216:219], v[10:13]
	v_mfma_f32_16x16x32_bf16 v[10:13], v[158:161], v[220:223], v[10:13]
	v_mfma_f32_16x16x32_bf16 v[14:17], v[150:153], v[220:223], v[14:17]
	v_mfma_f32_16x16x32_bf16 v[14:17], v[146:149], v[216:219], v[14:17]
	s_setprio 0
	s_barrier
	s_add_i32 s65, s65, 2
	s_add_u32 s76, s76, 0x100
	s_addc_u32 s77, s77, 0
	s_add_u32 s51, s51, 0x100
	s_addc_u32 s58, s58, 0
	s_cmp_gt_u32 s65, 29
	s_cbranch_scc1 .LBB0_264

.LBB0_285:
	s_add_u32 s0, s76, 0xfff80080
	s_addc_u32 s1, s77, -1
	s_and_b64 s[70:71], s[70:71], exec
	s_cselect_b32 vcc_hi, s21, s1
	s_cselect_b32 vcc_lo, s22, s0
	s_cselect_b32 s71, s23, s41
	s_cselect_b32 s70, s39, s7
	s_add_i32 s0, 0, 0x10000
	s_add_i32 s1, 0, 0x14000
	v_add_u32_e32 v146, s0, v1
	v_add_u32_e32 v174, s1, v1
	ds_read_b128 v[134:137], v146
	ds_read_b128 v[138:141], v146 offset:1024
	ds_read_b128 v[142:145], v146 offset:2048
	ds_read_b128 v[146:149], v146 offset:3072
	ds_read_b128 v[150:153], v174
	ds_read_b128 v[154:157], v174 offset:1024
	ds_read_b128 v[158:161], v174 offset:2048
	ds_read_b128 v[174:177], v174 offset:3072
	s_add_i32 m0, s67, 0xc000
	ds_read_b128 v[178:181], v222
	ds_read_b128 v[182:185], v222 offset:1024
	ds_read_b128 v[186:189], v222 offset:2048
	ds_read_b128 v[190:193], v222 offset:3072
	ds_read_b128 v[204:207], v222 offset:4096
	ds_read_b128 v[208:211], v222 offset:5120
	ds_read_b128 v[212:215], v222 offset:6144
	ds_read_b128 v[216:219], v222 offset:7168
	global_load_lds_dwordx4 v170, s[76:77]
	s_add_i32 m0, s67, 0xe000
	s_nop 0
	global_load_lds_dwordx4 v172, s[76:77]
	s_waitcnt vmcnt(8)
	s_waitcnt lgkmcnt(0)
	s_barrier
	s_setprio 1
	s_waitcnt lgkmcnt(0)
	v_mfma_f32_16x16x32_bf16 v[126:129], v[134:137], v[178:181], v[126:129]
	v_mfma_f32_16x16x32_bf16 v[126:129], v[138:141], v[182:185], v[126:129]
	v_mfma_f32_16x16x32_bf16 v[122:125], v[146:149], v[182:185], v[122:125]
	v_mfma_f32_16x16x32_bf16 v[122:125], v[142:145], v[178:181], v[122:125]
	v_mfma_f32_16x16x32_bf16 v[118:121], v[150:153], v[178:181], v[118:121]
	v_mfma_f32_16x16x32_bf16 v[118:121], v[154:157], v[182:185], v[118:121]
	v_mfma_f32_16x16x32_bf16 v[114:117], v[174:177], v[182:185], v[114:117]
	v_mfma_f32_16x16x32_bf16 v[114:117], v[158:161], v[178:181], v[114:117]
	v_mfma_f32_16x16x32_bf16 v[98:101], v[158:161], v[186:189], v[98:101]
	v_mfma_f32_16x16x32_bf16 v[98:101], v[174:177], v[190:193], v[98:101]
	v_mfma_f32_16x16x32_bf16 v[102:105], v[154:157], v[190:193], v[102:105]
	v_mfma_f32_16x16x32_bf16 v[102:105], v[150:153], v[186:189], v[102:105]
	v_mfma_f32_16x16x32_bf16 v[106:109], v[142:145], v[186:189], v[106:109]
	v_mfma_f32_16x16x32_bf16 v[106:109], v[146:149], v[190:193], v[106:109]
	v_mfma_f32_16x16x32_bf16 v[110:113], v[138:141], v[190:193], v[110:113]
	v_mfma_f32_16x16x32_bf16 v[110:113], v[134:137], v[186:189], v[110:113]
	v_mfma_f32_16x16x32_bf16 v[94:97], v[134:137], v[204:207], v[94:97]
	v_mfma_f32_16x16x32_bf16 v[94:97], v[138:141], v[208:211], v[94:97]
	v_mfma_f32_16x16x32_bf16 v[90:93], v[146:149], v[208:211], v[90:93]
	v_mfma_f32_16x16x32_bf16 v[90:93], v[142:145], v[204:207], v[90:93]
	v_mfma_f32_16x16x32_bf16 v[86:89], v[150:153], v[204:207], v[86:89]
	v_mfma_f32_16x16x32_bf16 v[86:89], v[154:157], v[208:211], v[86:89]
	v_mfma_f32_16x16x32_bf16 v[82:85], v[174:177], v[208:211], v[82:85]
	v_mfma_f32_16x16x32_bf16 v[82:85], v[158:161], v[204:207], v[82:85]
	v_mfma_f32_16x16x32_bf16 v[66:69], v[158:161], v[212:215], v[66:69]
	v_mfma_f32_16x16x32_bf16 v[66:69], v[174:177], v[216:219], v[66:69]
	v_mfma_f32_16x16x32_bf16 v[70:73], v[154:157], v[216:219], v[70:73]
	v_mfma_f32_16x16x32_bf16 v[70:73], v[150:153], v[212:215], v[70:73]
	v_mfma_f32_16x16x32_bf16 v[74:77], v[142:145], v[212:215], v[74:77]
	v_mfma_f32_16x16x32_bf16 v[74:77], v[146:149], v[216:219], v[74:77]
	v_mfma_f32_16x16x32_bf16 v[78:81], v[138:141], v[216:219], v[78:81]
	v_mfma_f32_16x16x32_bf16 v[78:81], v[134:137], v[212:215], v[78:81]
	s_setprio 0
	s_barrier
	s_add_i32 s0, s0, s54
	s_mov_b32 m0, s0
	ds_read_b128 v[178:181], v222 offset:16384
	ds_read_b128 v[182:185], v222 offset:17408
	ds_read_b128 v[186:189], v222 offset:18432
	ds_read_b128 v[190:193], v222 offset:19456
	ds_read_b128 v[204:207], v222 offset:20480
	ds_read_b128 v[208:211], v222 offset:21504
	ds_read_b128 v[212:215], v222 offset:22528
	ds_read_b128 v[216:219], v222 offset:23552
	global_load_lds_dwordx4 v164, s[70:71]
	s_add_i32 m0, s0, 0x2000
	s_add_u32 s44, s70, 0x80000
	s_addc_u32 s45, s71, 0
	s_add_i32 s0, s1, s54
	global_load_lds_dwordx4 v162, s[70:71]
	s_mov_b32 m0, s0
	s_nop 0
	global_load_lds_dwordx4 v164, s[44:45]
	s_add_i32 m0, s0, 0x2000
	s_nop 0
	global_load_lds_dwordx4 v162, s[44:45]
	s_mov_b32 m0, s67
	s_nop 0
	global_load_lds_dwordx4 v164, vcc
	s_mov_b32 m0, s68
	s_nop 0
	global_load_lds_dwordx4 v162, vcc
	s_waitcnt vmcnt(8)
	s_waitcnt lgkmcnt(0)
	s_barrier
	s_setprio 1
	s_waitcnt lgkmcnt(0)
	v_mfma_f32_16x16x32_bf16 v[62:65], v[134:137], v[178:181], v[62:65]
	v_mfma_f32_16x16x32_bf16 v[62:65], v[138:141], v[182:185], v[62:65]
	v_mfma_f32_16x16x32_bf16 v[58:61], v[146:149], v[182:185], v[58:61]
	v_mfma_f32_16x16x32_bf16 v[58:61], v[142:145], v[178:181], v[58:61]
	v_mfma_f32_16x16x32_bf16 v[54:57], v[150:153], v[178:181], v[54:57]
	v_mfma_f32_16x16x32_bf16 v[54:57], v[154:157], v[182:185], v[54:57]
	v_mfma_f32_16x16x32_bf16 v[50:53], v[174:177], v[182:185], v[50:53]
	v_mfma_f32_16x16x32_bf16 v[50:53], v[158:161], v[178:181], v[50:53]
	v_mfma_f32_16x16x32_bf16 v[34:37], v[158:161], v[186:189], v[34:37]
	v_mfma_f32_16x16x32_bf16 v[34:37], v[174:177], v[190:193], v[34:37]
	v_mfma_f32_16x16x32_bf16 v[38:41], v[154:157], v[190:193], v[38:41]
	v_mfma_f32_16x16x32_bf16 v[38:41], v[150:153], v[186:189], v[38:41]
	v_mfma_f32_16x16x32_bf16 v[42:45], v[142:145], v[186:189], v[42:45]
	v_mfma_f32_16x16x32_bf16 v[42:45], v[146:149], v[190:193], v[42:45]
	v_mfma_f32_16x16x32_bf16 v[46:49], v[138:141], v[190:193], v[46:49]
	v_mfma_f32_16x16x32_bf16 v[46:49], v[134:137], v[186:189], v[46:49]
	v_mfma_f32_16x16x32_bf16 v[30:33], v[134:137], v[204:207], v[30:33]
	v_mfma_f32_16x16x32_bf16 v[30:33], v[138:141], v[208:211], v[30:33]
	v_mfma_f32_16x16x32_bf16 v[26:29], v[146:149], v[208:211], v[26:29]
	v_mfma_f32_16x16x32_bf16 v[26:29], v[142:145], v[204:207], v[26:29]
	v_mfma_f32_16x16x32_bf16 v[22:25], v[150:153], v[204:207], v[22:25]
	v_mfma_f32_16x16x32_bf16 v[22:25], v[154:157], v[208:211], v[22:25]
	v_mfma_f32_16x16x32_bf16 v[18:21], v[174:177], v[208:211], v[18:21]
	v_mfma_f32_16x16x32_bf16 v[18:21], v[158:161], v[204:207], v[18:21]
	v_mfma_f32_16x16x32_bf16 v[2:5], v[158:161], v[212:215], v[2:5]
	v_mfma_f32_16x16x32_bf16 v[2:5], v[174:177], v[216:219], v[2:5]
	v_mfma_f32_16x16x32_bf16 v[6:9], v[154:157], v[216:219], v[6:9]
	v_mfma_f32_16x16x32_bf16 v[6:9], v[150:153], v[212:215], v[6:9]
	v_mfma_f32_16x16x32_bf16 v[10:13], v[142:145], v[212:215], v[10:13]
	v_mfma_f32_16x16x32_bf16 v[10:13], v[146:149], v[216:219], v[10:13]
	v_mfma_f32_16x16x32_bf16 v[14:17], v[138:141], v[216:219], v[14:17]
	v_mfma_f32_16x16x32_bf16 v[14:17], v[134:137], v[212:215], v[14:17]
	s_setprio 0
	s_barrier
	s_add_i32 s0, 0, 0x18000
	s_add_i32 s1, 0, 0x1c000
	v_add_u32_e32 v146, s0, v1
	v_add_u32_e32 v174, s1, v1
	ds_read_b128 v[134:137], v146
	ds_read_b128 v[138:141], v146 offset:1024
	ds_read_b128 v[142:145], v146 offset:2048
	ds_read_b128 v[146:149], v146 offset:3072
	ds_read_b128 v[150:153], v174
	ds_read_b128 v[154:157], v174 offset:1024
	ds_read_b128 v[158:161], v174 offset:2048
	ds_read_b128 v[174:177], v174 offset:3072
	s_add_u32 s44, vcc_lo, 0x80000
	s_addc_u32 s45, vcc_hi, 0
	s_mov_b32 m0, s8
	ds_read_b128 v[178:181], v222 offset:32768
	ds_read_b128 v[182:185], v222 offset:33792
	ds_read_b128 v[186:189], v222 offset:34816
	ds_read_b128 v[190:193], v222 offset:35840
	ds_read_b128 v[204:207], v222 offset:36864
	ds_read_b128 v[208:211], v222 offset:37888
	ds_read_b128 v[212:215], v222 offset:38912
	ds_read_b128 v[216:219], v222 offset:39936
	global_load_lds_dwordx4 v164, s[44:45]
	s_mov_b32 m0, s9
	s_nop 0
	global_load_lds_dwordx4 v162, s[44:45]
	s_waitcnt vmcnt(8)
	s_waitcnt lgkmcnt(0)
	s_barrier
	s_setprio 1
	s_waitcnt lgkmcnt(0)
	v_mfma_f32_16x16x32_bf16 v[126:129], v[134:137], v[178:181], v[126:129]
	v_mfma_f32_16x16x32_bf16 v[126:129], v[138:141], v[182:185], v[126:129]
	v_mfma_f32_16x16x32_bf16 v[122:125], v[146:149], v[182:185], v[122:125]
	v_mfma_f32_16x16x32_bf16 v[122:125], v[142:145], v[178:181], v[122:125]
	v_mfma_f32_16x16x32_bf16 v[118:121], v[150:153], v[178:181], v[118:121]
	v_mfma_f32_16x16x32_bf16 v[118:121], v[154:157], v[182:185], v[118:121]
	v_mfma_f32_16x16x32_bf16 v[114:117], v[174:177], v[182:185], v[114:117]
	v_mfma_f32_16x16x32_bf16 v[114:117], v[158:161], v[178:181], v[114:117]
	v_mfma_f32_16x16x32_bf16 v[98:101], v[158:161], v[186:189], v[98:101]
	v_mfma_f32_16x16x32_bf16 v[98:101], v[174:177], v[190:193], v[98:101]
	v_mfma_f32_16x16x32_bf16 v[102:105], v[154:157], v[190:193], v[102:105]
	v_mfma_f32_16x16x32_bf16 v[102:105], v[150:153], v[186:189], v[102:105]
	v_mfma_f32_16x16x32_bf16 v[106:109], v[142:145], v[186:189], v[106:109]
	v_mfma_f32_16x16x32_bf16 v[106:109], v[146:149], v[190:193], v[106:109]
	v_mfma_f32_16x16x32_bf16 v[110:113], v[138:141], v[190:193], v[110:113]
	v_mfma_f32_16x16x32_bf16 v[110:113], v[134:137], v[186:189], v[110:113]
	v_mfma_f32_16x16x32_bf16 v[94:97], v[134:137], v[204:207], v[94:97]
	v_mfma_f32_16x16x32_bf16 v[94:97], v[138:141], v[208:211], v[94:97]
	v_mfma_f32_16x16x32_bf16 v[90:93], v[146:149], v[208:211], v[90:93]
	v_mfma_f32_16x16x32_bf16 v[90:93], v[142:145], v[204:207], v[90:93]
	v_mfma_f32_16x16x32_bf16 v[86:89], v[150:153], v[204:207], v[86:89]
	v_mfma_f32_16x16x32_bf16 v[86:89], v[154:157], v[208:211], v[86:89]
	v_mfma_f32_16x16x32_bf16 v[82:85], v[174:177], v[208:211], v[82:85]
	v_mfma_f32_16x16x32_bf16 v[82:85], v[158:161], v[204:207], v[82:85]
	v_mfma_f32_16x16x32_bf16 v[66:69], v[158:161], v[212:215], v[66:69]
	v_mfma_f32_16x16x32_bf16 v[66:69], v[174:177], v[216:219], v[66:69]
	v_mfma_f32_16x16x32_bf16 v[70:73], v[154:157], v[216:219], v[70:73]
	v_mfma_f32_16x16x32_bf16 v[70:73], v[150:153], v[212:215], v[70:73]
	v_mfma_f32_16x16x32_bf16 v[74:77], v[142:145], v[212:215], v[74:77]
	v_mfma_f32_16x16x32_bf16 v[74:77], v[146:149], v[216:219], v[74:77]
	v_mfma_f32_16x16x32_bf16 v[78:81], v[138:141], v[216:219], v[78:81]
	v_mfma_f32_16x16x32_bf16 v[78:81], v[134:137], v[212:215], v[78:81]
	s_setprio 0
	s_barrier
	s_add_u32 s98, s70, 0x80
	s_addc_u32 s99, s71, 0
	s_add_u32 s100, vcc_lo, 0x80
	s_addc_u32 s101, vcc_hi, 0
	s_add_i32 s0, s0, s54
	s_mov_b32 m0, s0
	ds_read_b128 v[178:181], v222 offset:49152
	ds_read_b128 v[182:185], v222 offset:50176
	ds_read_b128 v[186:189], v222 offset:51200
	ds_read_b128 v[190:193], v222 offset:52224
	ds_read_b128 v[204:207], v222 offset:53248
	ds_read_b128 v[208:211], v222 offset:54272
	ds_read_b128 v[212:215], v222 offset:55296
	ds_read_b128 v[216:219], v222 offset:56320
	global_load_lds_dwordx4 v164, s[98:99]
	s_add_i32 m0, s0, 0x2000
	s_add_u32 s44, s70, 0x80080
	s_addc_u32 s45, s71, 0
	s_add_i32 s0, s1, s54
	global_load_lds_dwordx4 v162, s[98:99]
	s_mov_b32 m0, s0
	s_nop 0
	global_load_lds_dwordx4 v164, s[44:45]
	s_add_i32 m0, s0, 0x2000
	s_nop 0
	global_load_lds_dwordx4 v162, s[44:45]
	s_mov_b32 m0, s27
	s_nop 0
	global_load_lds_dwordx4 v164, s[100:101]
	s_mov_b32 m0, s26
	s_nop 0
	global_load_lds_dwordx4 v162, s[100:101]
	s_waitcnt vmcnt(8)
	s_waitcnt lgkmcnt(0)
	s_barrier
	s_setprio 1
	s_waitcnt lgkmcnt(0)
	v_mfma_f32_16x16x32_bf16 v[62:65], v[134:137], v[178:181], v[62:65]
	v_mfma_f32_16x16x32_bf16 v[62:65], v[138:141], v[182:185], v[62:65]
	v_mfma_f32_16x16x32_bf16 v[58:61], v[146:149], v[182:185], v[58:61]
	v_mfma_f32_16x16x32_bf16 v[58:61], v[142:145], v[178:181], v[58:61]
	v_mfma_f32_16x16x32_bf16 v[54:57], v[150:153], v[178:181], v[54:57]
	v_mfma_f32_16x16x32_bf16 v[54:57], v[154:157], v[182:185], v[54:57]
	v_mfma_f32_16x16x32_bf16 v[50:53], v[174:177], v[182:185], v[50:53]
	v_mfma_f32_16x16x32_bf16 v[50:53], v[158:161], v[178:181], v[50:53]
	v_mfma_f32_16x16x32_bf16 v[34:37], v[158:161], v[186:189], v[34:37]
	v_mfma_f32_16x16x32_bf16 v[34:37], v[174:177], v[190:193], v[34:37]
	v_mfma_f32_16x16x32_bf16 v[38:41], v[154:157], v[190:193], v[38:41]
	v_mfma_f32_16x16x32_bf16 v[38:41], v[150:153], v[186:189], v[38:41]
	v_mfma_f32_16x16x32_bf16 v[42:45], v[142:145], v[186:189], v[42:45]
	v_mfma_f32_16x16x32_bf16 v[42:45], v[146:149], v[190:193], v[42:45]
	v_mfma_f32_16x16x32_bf16 v[46:49], v[138:141], v[190:193], v[46:49]
	v_mfma_f32_16x16x32_bf16 v[46:49], v[134:137], v[186:189], v[46:49]
	v_mfma_f32_16x16x32_bf16 v[30:33], v[134:137], v[204:207], v[30:33]
	v_mfma_f32_16x16x32_bf16 v[30:33], v[138:141], v[208:211], v[30:33]
	v_mfma_f32_16x16x32_bf16 v[26:29], v[146:149], v[208:211], v[26:29]
	v_mfma_f32_16x16x32_bf16 v[26:29], v[142:145], v[204:207], v[26:29]
	v_mfma_f32_16x16x32_bf16 v[22:25], v[150:153], v[204:207], v[22:25]
	v_mfma_f32_16x16x32_bf16 v[22:25], v[154:157], v[208:211], v[22:25]
	v_mfma_f32_16x16x32_bf16 v[18:21], v[174:177], v[208:211], v[18:21]
	v_mfma_f32_16x16x32_bf16 v[18:21], v[158:161], v[204:207], v[18:21]
	v_mfma_f32_16x16x32_bf16 v[2:5], v[158:161], v[212:215], v[2:5]
	v_mfma_f32_16x16x32_bf16 v[2:5], v[174:177], v[216:219], v[2:5]
	v_mfma_f32_16x16x32_bf16 v[6:9], v[154:157], v[216:219], v[6:9]
	v_mfma_f32_16x16x32_bf16 v[6:9], v[150:153], v[212:215], v[6:9]
	v_mfma_f32_16x16x32_bf16 v[10:13], v[142:145], v[212:215], v[10:13]
	v_mfma_f32_16x16x32_bf16 v[10:13], v[146:149], v[216:219], v[10:13]
	v_mfma_f32_16x16x32_bf16 v[14:17], v[138:141], v[216:219], v[14:17]
	v_mfma_f32_16x16x32_bf16 v[14:17], v[134:137], v[212:215], v[14:17]
	s_setprio 0
	s_barrier
	s_add_i32 s43, s43, 2
	s_add_u32 s76, s76, 0x100
	s_addc_u32 s77, s77, 0
	s_add_u32 s7, s7, 0x100
	s_addc_u32 s41, s41, 0
	s_cmp_gt_u32 s43, 29
	s_cbranch_scc1 .LBB0_288

.LBB0_509:
	s_add_u32 s90, s76, 0x100
	s_addc_u32 s91, s77, 0
	s_and_b64 s[0:1], s[70:71], exec
	s_cselect_b32 vcc_hi, s22, s91
	s_cselect_b32 vcc_lo, s23, s90
	s_cselect_b32 s71, s41, s53
	s_cselect_b32 s70, s44, s51
	s_add_i32 s0, 0, 0x10000
	s_add_i32 s18, 0, 0x14000
	v_add_u32_e32 v114, s0, v1
	v_add_u32_e32 v154, s18, v1
	ds_read_b128 v[78:81], v114
	ds_read_b128 v[90:93], v114 offset:1024
	ds_read_b128 v[102:105], v114 offset:2048
	ds_read_b128 v[114:117], v114 offset:3072
	ds_read_b128 v[126:129], v154
	ds_read_b128 v[134:137], v154 offset:1024
	ds_read_b128 v[142:145], v154 offset:2048
	ds_read_b128 v[154:157], v154 offset:3072
	s_add_i32 m0, s29, 0xc000
	ds_read_b128 v[158:161], v237
	ds_read_b128 v[162:165], v237 offset:1024
	ds_read_b128 v[166:169], v237 offset:2048
	ds_read_b128 v[178:181], v237 offset:3072
	ds_read_b128 v[182:185], v237 offset:4096
	ds_read_b128 v[186:189], v237 offset:5120
	ds_read_b128 v[190:193], v237 offset:6144
	ds_read_b128 v[214:217], v237 offset:7168
	global_load_lds_dwordx4 v210, s[76:77]
	s_add_i32 m0, s29, 0xe000
	s_nop 0
	global_load_lds_dwordx4 v212, s[76:77]
	s_waitcnt vmcnt(8)
	s_waitcnt lgkmcnt(0)
	s_barrier
	s_setprio 1
	s_waitcnt lgkmcnt(0)
	v_mfma_f32_16x16x32_bf16 v[174:177], v[78:81], v[158:161], v[174:177]
	v_mfma_f32_16x16x32_bf16 v[174:177], v[90:93], v[162:165], v[174:177]
	v_mfma_f32_16x16x32_bf16 v[170:173], v[114:117], v[162:165], v[170:173]
	v_mfma_f32_16x16x32_bf16 v[170:173], v[102:105], v[158:161], v[170:173]
	v_mfma_f32_16x16x32_bf16 v[150:153], v[126:129], v[158:161], v[150:153]
	v_mfma_f32_16x16x32_bf16 v[150:153], v[134:137], v[162:165], v[150:153]
	v_mfma_f32_16x16x32_bf16 v[146:149], v[154:157], v[162:165], v[146:149]
	v_mfma_f32_16x16x32_bf16 v[146:149], v[142:145], v[158:161], v[146:149]
	v_mfma_f32_16x16x32_bf16 v[118:121], v[142:145], v[166:169], v[118:121]
	v_mfma_f32_16x16x32_bf16 v[118:121], v[154:157], v[178:181], v[118:121]
	v_mfma_f32_16x16x32_bf16 v[122:125], v[134:137], v[178:181], v[122:125]
	v_mfma_f32_16x16x32_bf16 v[122:125], v[126:129], v[166:169], v[122:125]
	v_mfma_f32_16x16x32_bf16 v[130:133], v[102:105], v[166:169], v[130:133]
	v_mfma_f32_16x16x32_bf16 v[130:133], v[114:117], v[178:181], v[130:133]
	v_mfma_f32_16x16x32_bf16 v[138:141], v[90:93], v[178:181], v[138:141]
	v_mfma_f32_16x16x32_bf16 v[138:141], v[78:81], v[166:169], v[138:141]
	v_mfma_f32_16x16x32_bf16 v[110:113], v[78:81], v[182:185], v[110:113]
	v_mfma_f32_16x16x32_bf16 v[110:113], v[90:93], v[186:189], v[110:113]
	v_mfma_f32_16x16x32_bf16 v[106:109], v[114:117], v[186:189], v[106:109]
	v_mfma_f32_16x16x32_bf16 v[106:109], v[102:105], v[182:185], v[106:109]
	v_mfma_f32_16x16x32_bf16 v[98:101], v[126:129], v[182:185], v[98:101]
	v_mfma_f32_16x16x32_bf16 v[98:101], v[134:137], v[186:189], v[98:101]
	v_mfma_f32_16x16x32_bf16 v[94:97], v[154:157], v[186:189], v[94:97]
	v_mfma_f32_16x16x32_bf16 v[94:97], v[142:145], v[182:185], v[94:97]
	v_mfma_f32_16x16x32_bf16 v[66:69], v[142:145], v[190:193], v[66:69]
	v_mfma_f32_16x16x32_bf16 v[66:69], v[154:157], v[214:217], v[66:69]
	v_mfma_f32_16x16x32_bf16 v[74:77], v[134:137], v[214:217], v[74:77]
	v_mfma_f32_16x16x32_bf16 v[74:77], v[126:129], v[190:193], v[74:77]
	v_mfma_f32_16x16x32_bf16 v[82:85], v[102:105], v[190:193], v[82:85]
	v_mfma_f32_16x16x32_bf16 v[82:85], v[114:117], v[214:217], v[82:85]
	v_mfma_f32_16x16x32_bf16 v[86:89], v[90:93], v[214:217], v[86:89]
	v_mfma_f32_16x16x32_bf16 v[86:89], v[78:81], v[190:193], v[86:89]
	s_setprio 0
	s_barrier
	s_add_i32 s0, s0, s28
	s_mov_b32 m0, s0
	ds_read_b128 v[158:161], v237 offset:16384
	ds_read_b128 v[162:165], v237 offset:17408
	ds_read_b128 v[166:169], v237 offset:18432
	ds_read_b128 v[178:181], v237 offset:19456
	ds_read_b128 v[182:185], v237 offset:20480
	ds_read_b128 v[186:189], v237 offset:21504
	ds_read_b128 v[190:193], v237 offset:22528
	ds_read_b128 v[214:217], v237 offset:23552
	global_load_lds_dwordx4 v194, s[70:71]
	s_add_i32 m0, s0, 0x2000
	s_add_u32 s0, s70, 0x80000
	s_addc_u32 s1, s71, 0
	s_add_i32 s18, s18, s28
	global_load_lds_dwordx4 v204, s[70:71]
	s_mov_b32 m0, s18
	s_nop 0
	global_load_lds_dwordx4 v194, s[0:1]
	s_add_i32 m0, s18, 0x2000
	s_nop 0
	global_load_lds_dwordx4 v204, s[0:1]
	s_mov_b32 m0, s29
	s_nop 0
	global_load_lds_dwordx4 v194, vcc
	s_mov_b32 m0, s31
	s_nop 0
	global_load_lds_dwordx4 v204, vcc
	s_waitcnt vmcnt(8)
	s_waitcnt lgkmcnt(0)
	s_barrier
	s_setprio 1
	s_waitcnt lgkmcnt(0)
	v_mfma_f32_16x16x32_bf16 v[62:65], v[78:81], v[158:161], v[62:65]
	v_mfma_f32_16x16x32_bf16 v[62:65], v[90:93], v[162:165], v[62:65]
	v_mfma_f32_16x16x32_bf16 v[58:61], v[114:117], v[162:165], v[58:61]
	v_mfma_f32_16x16x32_bf16 v[58:61], v[102:105], v[158:161], v[58:61]
	v_mfma_f32_16x16x32_bf16 v[54:57], v[126:129], v[158:161], v[54:57]
	v_mfma_f32_16x16x32_bf16 v[54:57], v[134:137], v[162:165], v[54:57]
	v_mfma_f32_16x16x32_bf16 v[50:53], v[154:157], v[162:165], v[50:53]
	v_mfma_f32_16x16x32_bf16 v[50:53], v[142:145], v[158:161], v[50:53]
	v_mfma_f32_16x16x32_bf16 v[34:37], v[142:145], v[166:169], v[34:37]
	v_mfma_f32_16x16x32_bf16 v[34:37], v[154:157], v[178:181], v[34:37]
	v_mfma_f32_16x16x32_bf16 v[38:41], v[134:137], v[178:181], v[38:41]
	v_mfma_f32_16x16x32_bf16 v[38:41], v[126:129], v[166:169], v[38:41]
	v_mfma_f32_16x16x32_bf16 v[42:45], v[102:105], v[166:169], v[42:45]
	v_mfma_f32_16x16x32_bf16 v[42:45], v[114:117], v[178:181], v[42:45]
	v_mfma_f32_16x16x32_bf16 v[46:49], v[90:93], v[178:181], v[46:49]
	v_mfma_f32_16x16x32_bf16 v[46:49], v[78:81], v[166:169], v[46:49]
	v_mfma_f32_16x16x32_bf16 v[30:33], v[78:81], v[182:185], v[30:33]
	v_mfma_f32_16x16x32_bf16 v[30:33], v[90:93], v[186:189], v[30:33]
	v_mfma_f32_16x16x32_bf16 v[26:29], v[114:117], v[186:189], v[26:29]
	v_mfma_f32_16x16x32_bf16 v[26:29], v[102:105], v[182:185], v[26:29]
	v_mfma_f32_16x16x32_bf16 v[22:25], v[126:129], v[182:185], v[22:25]
	v_mfma_f32_16x16x32_bf16 v[22:25], v[134:137], v[186:189], v[22:25]
	v_mfma_f32_16x16x32_bf16 v[18:21], v[154:157], v[186:189], v[18:21]
	v_mfma_f32_16x16x32_bf16 v[18:21], v[142:145], v[182:185], v[18:21]
	v_mfma_f32_16x16x32_bf16 v[2:5], v[142:145], v[190:193], v[2:5]
	v_mfma_f32_16x16x32_bf16 v[2:5], v[154:157], v[214:217], v[2:5]
	v_mfma_f32_16x16x32_bf16 v[6:9], v[134:137], v[214:217], v[6:9]
	v_mfma_f32_16x16x32_bf16 v[6:9], v[126:129], v[190:193], v[6:9]
	v_mfma_f32_16x16x32_bf16 v[10:13], v[102:105], v[190:193], v[10:13]
	v_mfma_f32_16x16x32_bf16 v[10:13], v[114:117], v[214:217], v[10:13]
	v_mfma_f32_16x16x32_bf16 v[14:17], v[90:93], v[214:217], v[14:17]
	v_mfma_f32_16x16x32_bf16 v[14:17], v[78:81], v[190:193], v[14:17]
	s_setprio 0
	s_barrier
	s_add_i32 s18, 0, 0x18000
	s_add_i32 s19, 0, 0x1c000
	v_add_u32_e32 v114, s18, v1
	v_add_u32_e32 v154, s19, v1
	ds_read_b128 v[78:81], v114
	ds_read_b128 v[90:93], v114 offset:1024
	ds_read_b128 v[102:105], v114 offset:2048
	ds_read_b128 v[114:117], v114 offset:3072
	ds_read_b128 v[126:129], v154
	ds_read_b128 v[134:137], v154 offset:1024
	ds_read_b128 v[142:145], v154 offset:2048
	ds_read_b128 v[154:157], v154 offset:3072
	s_add_u32 s0, vcc_lo, 0x80000
	s_addc_u32 s1, vcc_hi, 0
	s_mov_b32 m0, s33
	ds_read_b128 v[158:161], v237 offset:32768
	ds_read_b128 v[162:165], v237 offset:33792
	ds_read_b128 v[166:169], v237 offset:34816
	ds_read_b128 v[178:181], v237 offset:35840
	ds_read_b128 v[182:185], v237 offset:36864
	ds_read_b128 v[186:189], v237 offset:37888
	ds_read_b128 v[190:193], v237 offset:38912
	ds_read_b128 v[214:217], v237 offset:39936
	global_load_lds_dwordx4 v194, s[0:1]
	s_mov_b32 m0, s43
	s_nop 0
	global_load_lds_dwordx4 v204, s[0:1]
	s_waitcnt vmcnt(8)
	s_waitcnt lgkmcnt(0)
	s_barrier
	s_setprio 1
	s_waitcnt lgkmcnt(0)
	v_mfma_f32_16x16x32_bf16 v[174:177], v[78:81], v[158:161], v[174:177]
	v_mfma_f32_16x16x32_bf16 v[174:177], v[90:93], v[162:165], v[174:177]
	v_mfma_f32_16x16x32_bf16 v[170:173], v[114:117], v[162:165], v[170:173]
	v_mfma_f32_16x16x32_bf16 v[170:173], v[102:105], v[158:161], v[170:173]
	v_mfma_f32_16x16x32_bf16 v[150:153], v[126:129], v[158:161], v[150:153]
	v_mfma_f32_16x16x32_bf16 v[150:153], v[134:137], v[162:165], v[150:153]
	v_mfma_f32_16x16x32_bf16 v[146:149], v[154:157], v[162:165], v[146:149]
	v_mfma_f32_16x16x32_bf16 v[146:149], v[142:145], v[158:161], v[146:149]
	v_mfma_f32_16x16x32_bf16 v[118:121], v[142:145], v[166:169], v[118:121]
	v_mfma_f32_16x16x32_bf16 v[118:121], v[154:157], v[178:181], v[118:121]
	v_mfma_f32_16x16x32_bf16 v[122:125], v[134:137], v[178:181], v[122:125]
	v_mfma_f32_16x16x32_bf16 v[122:125], v[126:129], v[166:169], v[122:125]
	v_mfma_f32_16x16x32_bf16 v[130:133], v[102:105], v[166:169], v[130:133]
	v_mfma_f32_16x16x32_bf16 v[130:133], v[114:117], v[178:181], v[130:133]
	v_mfma_f32_16x16x32_bf16 v[138:141], v[90:93], v[178:181], v[138:141]
	v_mfma_f32_16x16x32_bf16 v[138:141], v[78:81], v[166:169], v[138:141]
	v_mfma_f32_16x16x32_bf16 v[110:113], v[78:81], v[182:185], v[110:113]
	v_mfma_f32_16x16x32_bf16 v[110:113], v[90:93], v[186:189], v[110:113]
	v_mfma_f32_16x16x32_bf16 v[106:109], v[114:117], v[186:189], v[106:109]
	v_mfma_f32_16x16x32_bf16 v[106:109], v[102:105], v[182:185], v[106:109]
	v_mfma_f32_16x16x32_bf16 v[98:101], v[126:129], v[182:185], v[98:101]
	v_mfma_f32_16x16x32_bf16 v[98:101], v[134:137], v[186:189], v[98:101]
	v_mfma_f32_16x16x32_bf16 v[94:97], v[154:157], v[186:189], v[94:97]
	v_mfma_f32_16x16x32_bf16 v[94:97], v[142:145], v[182:185], v[94:97]
	v_mfma_f32_16x16x32_bf16 v[66:69], v[142:145], v[190:193], v[66:69]
	v_mfma_f32_16x16x32_bf16 v[66:69], v[154:157], v[214:217], v[66:69]
	v_mfma_f32_16x16x32_bf16 v[74:77], v[134:137], v[214:217], v[74:77]
	v_mfma_f32_16x16x32_bf16 v[74:77], v[126:129], v[190:193], v[74:77]
	v_mfma_f32_16x16x32_bf16 v[82:85], v[102:105], v[190:193], v[82:85]
	v_mfma_f32_16x16x32_bf16 v[82:85], v[114:117], v[214:217], v[82:85]
	v_mfma_f32_16x16x32_bf16 v[86:89], v[90:93], v[214:217], v[86:89]
	v_mfma_f32_16x16x32_bf16 v[86:89], v[78:81], v[190:193], v[86:89]
	s_setprio 0
	s_barrier
	s_add_u32 s98, s70, 0x80
	s_addc_u32 s99, s71, 0
	s_add_u32 s100, vcc_lo, 0x80
	s_addc_u32 s101, vcc_hi, 0
	s_add_i32 s0, s18, s28
	s_mov_b32 m0, s0
	ds_read_b128 v[158:161], v237 offset:49152
	ds_read_b128 v[162:165], v237 offset:50176
	ds_read_b128 v[166:169], v237 offset:51200
	ds_read_b128 v[178:181], v237 offset:52224
	ds_read_b128 v[182:185], v237 offset:53248
	ds_read_b128 v[186:189], v237 offset:54272
	ds_read_b128 v[190:193], v237 offset:55296
	ds_read_b128 v[214:217], v237 offset:56320
	global_load_lds_dwordx4 v194, s[98:99]
	s_add_i32 m0, s0, 0x2000
	s_add_u32 s0, s70, 0x80080
	s_addc_u32 s1, s71, 0
	s_add_i32 s18, s19, s28
	global_load_lds_dwordx4 v204, s[98:99]
	s_mov_b32 m0, s18
	s_nop 0
	global_load_lds_dwordx4 v194, s[0:1]
	s_add_i32 m0, s18, 0x2000
	s_nop 0
	global_load_lds_dwordx4 v204, s[0:1]
	s_mov_b32 m0, s68
	s_nop 0
	global_load_lds_dwordx4 v194, s[100:101]
	s_mov_b32 m0, s79
	s_nop 0
	global_load_lds_dwordx4 v204, s[100:101]
	s_waitcnt vmcnt(8)
	s_waitcnt lgkmcnt(0)
	s_barrier
	s_setprio 1
	s_waitcnt lgkmcnt(0)
	v_mfma_f32_16x16x32_bf16 v[62:65], v[78:81], v[158:161], v[62:65]
	v_mfma_f32_16x16x32_bf16 v[62:65], v[90:93], v[162:165], v[62:65]
	v_mfma_f32_16x16x32_bf16 v[58:61], v[114:117], v[162:165], v[58:61]
	v_mfma_f32_16x16x32_bf16 v[58:61], v[102:105], v[158:161], v[58:61]
	v_mfma_f32_16x16x32_bf16 v[54:57], v[126:129], v[158:161], v[54:57]
	v_mfma_f32_16x16x32_bf16 v[54:57], v[134:137], v[162:165], v[54:57]
	v_mfma_f32_16x16x32_bf16 v[50:53], v[154:157], v[162:165], v[50:53]
	v_mfma_f32_16x16x32_bf16 v[50:53], v[142:145], v[158:161], v[50:53]
	v_mfma_f32_16x16x32_bf16 v[34:37], v[142:145], v[166:169], v[34:37]
	v_mfma_f32_16x16x32_bf16 v[34:37], v[154:157], v[178:181], v[34:37]
	v_mfma_f32_16x16x32_bf16 v[38:41], v[134:137], v[178:181], v[38:41]
	v_mfma_f32_16x16x32_bf16 v[38:41], v[126:129], v[166:169], v[38:41]
	v_mfma_f32_16x16x32_bf16 v[42:45], v[102:105], v[166:169], v[42:45]
	v_mfma_f32_16x16x32_bf16 v[42:45], v[114:117], v[178:181], v[42:45]
	v_mfma_f32_16x16x32_bf16 v[46:49], v[90:93], v[178:181], v[46:49]
	v_mfma_f32_16x16x32_bf16 v[46:49], v[78:81], v[166:169], v[46:49]
	v_mfma_f32_16x16x32_bf16 v[30:33], v[78:81], v[182:185], v[30:33]
	v_mfma_f32_16x16x32_bf16 v[30:33], v[90:93], v[186:189], v[30:33]
	v_mfma_f32_16x16x32_bf16 v[26:29], v[114:117], v[186:189], v[26:29]
	v_mfma_f32_16x16x32_bf16 v[26:29], v[102:105], v[182:185], v[26:29]
	v_mfma_f32_16x16x32_bf16 v[22:25], v[126:129], v[182:185], v[22:25]
	v_mfma_f32_16x16x32_bf16 v[22:25], v[134:137], v[186:189], v[22:25]
	v_mfma_f32_16x16x32_bf16 v[18:21], v[154:157], v[186:189], v[18:21]
	v_mfma_f32_16x16x32_bf16 v[18:21], v[142:145], v[182:185], v[18:21]
	v_mfma_f32_16x16x32_bf16 v[2:5], v[142:145], v[190:193], v[2:5]
	v_mfma_f32_16x16x32_bf16 v[2:5], v[154:157], v[214:217], v[2:5]
	v_mfma_f32_16x16x32_bf16 v[6:9], v[134:137], v[214:217], v[6:9]
	v_mfma_f32_16x16x32_bf16 v[6:9], v[126:129], v[190:193], v[6:9]
	v_mfma_f32_16x16x32_bf16 v[10:13], v[102:105], v[190:193], v[10:13]
	v_mfma_f32_16x16x32_bf16 v[10:13], v[114:117], v[214:217], v[10:13]
	v_mfma_f32_16x16x32_bf16 v[14:17], v[90:93], v[214:217], v[14:17]
	v_mfma_f32_16x16x32_bf16 v[14:17], v[78:81], v[190:193], v[14:17]
	s_setprio 0
	s_barrier
	s_add_i32 s57, s57, 2
	s_add_u32 s51, s51, 0x100
	s_addc_u32 s53, s53, 0
	s_cmp_gt_u32 s57, 29
	s_mov_b64 s[76:77], s[90:91]
	s_cbranch_scc1 .LBB0_512

.LBB0_581:
	s_add_u32 s18, s62, 0xfff80080
	s_addc_u32 s19, s63, -1
	s_and_b64 s[0:1], s[64:65], exec
	s_cselect_b32 s71, s22, s19
	s_cselect_b32 s70, s23, s18
	s_cselect_b32 s65, s39, s58
	s_cselect_b32 s64, s47, s53
	s_add_i32 s0, 0, 0x10000
	v_add_u32_e32 v153, s0, v1
	s_add_i32 s18, 0, 0x14000
	ds_read_b128 v[144:147], v153
	ds_read_b128 v[148:151], v153 offset:1024
	ds_read_b128 v[154:157], v153 offset:2048
	ds_read_b128 v[158:161], v153 offset:3072
	v_add_u32_e32 v153, s18, v1
	ds_read_b128 v[162:165], v153
	ds_read_b128 v[166:169], v153 offset:1024
	ds_read_b128 v[170:173], v153 offset:2048
	ds_read_b128 v[174:177], v153 offset:3072
	s_add_i32 m0, s29, 0xc000
	ds_read_b128 v[178:181], v152
	ds_read_b128 v[182:185], v152 offset:1024
	ds_read_b128 v[186:189], v152 offset:2048
	ds_read_b128 v[190:193], v152 offset:3072
	ds_read_b128 v[204:207], v152 offset:4096
	ds_read_b128 v[208:211], v152 offset:5120
	ds_read_b128 v[212:215], v152 offset:6144
	ds_read_b128 v[216:219], v152 offset:7168
	global_load_lds_dwordx4 v136, s[62:63]
	s_add_i32 m0, s29, 0xe000
	s_nop 0
	global_load_lds_dwordx4 v138, s[62:63]
	s_waitcnt vmcnt(8)
	s_waitcnt lgkmcnt(0)
	s_barrier
	s_setprio 1
	s_waitcnt lgkmcnt(0)
	v_mfma_f32_16x16x32_bf16 v[126:129], v[144:147], v[178:181], v[126:129]
	v_mfma_f32_16x16x32_bf16 v[126:129], v[148:151], v[182:185], v[126:129]
	v_mfma_f32_16x16x32_bf16 v[122:125], v[158:161], v[182:185], v[122:125]
	v_mfma_f32_16x16x32_bf16 v[122:125], v[154:157], v[178:181], v[122:125]
	v_mfma_f32_16x16x32_bf16 v[118:121], v[162:165], v[178:181], v[118:121]
	v_mfma_f32_16x16x32_bf16 v[118:121], v[166:169], v[182:185], v[118:121]
	v_mfma_f32_16x16x32_bf16 v[114:117], v[174:177], v[182:185], v[114:117]
	v_mfma_f32_16x16x32_bf16 v[114:117], v[170:173], v[178:181], v[114:117]
	v_mfma_f32_16x16x32_bf16 v[98:101], v[170:173], v[186:189], v[98:101]
	v_mfma_f32_16x16x32_bf16 v[98:101], v[174:177], v[190:193], v[98:101]
	v_mfma_f32_16x16x32_bf16 v[102:105], v[166:169], v[190:193], v[102:105]
	v_mfma_f32_16x16x32_bf16 v[102:105], v[162:165], v[186:189], v[102:105]
	v_mfma_f32_16x16x32_bf16 v[106:109], v[154:157], v[186:189], v[106:109]
	v_mfma_f32_16x16x32_bf16 v[106:109], v[158:161], v[190:193], v[106:109]
	v_mfma_f32_16x16x32_bf16 v[110:113], v[148:151], v[190:193], v[110:113]
	v_mfma_f32_16x16x32_bf16 v[110:113], v[144:147], v[186:189], v[110:113]
	v_mfma_f32_16x16x32_bf16 v[94:97], v[144:147], v[204:207], v[94:97]
	v_mfma_f32_16x16x32_bf16 v[94:97], v[148:151], v[208:211], v[94:97]
	v_mfma_f32_16x16x32_bf16 v[90:93], v[158:161], v[208:211], v[90:93]
	v_mfma_f32_16x16x32_bf16 v[90:93], v[154:157], v[204:207], v[90:93]
	v_mfma_f32_16x16x32_bf16 v[86:89], v[162:165], v[204:207], v[86:89]
	v_mfma_f32_16x16x32_bf16 v[86:89], v[166:169], v[208:211], v[86:89]
	v_mfma_f32_16x16x32_bf16 v[82:85], v[174:177], v[208:211], v[82:85]
	v_mfma_f32_16x16x32_bf16 v[82:85], v[170:173], v[204:207], v[82:85]
	v_mfma_f32_16x16x32_bf16 v[66:69], v[170:173], v[212:215], v[66:69]
	v_mfma_f32_16x16x32_bf16 v[66:69], v[174:177], v[216:219], v[66:69]
	v_mfma_f32_16x16x32_bf16 v[70:73], v[166:169], v[216:219], v[70:73]
	v_mfma_f32_16x16x32_bf16 v[70:73], v[162:165], v[212:215], v[70:73]
	v_mfma_f32_16x16x32_bf16 v[74:77], v[154:157], v[212:215], v[74:77]
	v_mfma_f32_16x16x32_bf16 v[74:77], v[158:161], v[216:219], v[74:77]
	v_mfma_f32_16x16x32_bf16 v[78:81], v[148:151], v[216:219], v[78:81]
	v_mfma_f32_16x16x32_bf16 v[78:81], v[144:147], v[212:215], v[78:81]
	s_setprio 0
	s_barrier
	s_add_i32 s0, s0, s28
	s_mov_b32 m0, s0
	ds_read_b128 v[178:181], v152 offset:16384
	ds_read_b128 v[182:185], v152 offset:17408
	ds_read_b128 v[186:189], v152 offset:18432
	ds_read_b128 v[190:193], v152 offset:19456
	ds_read_b128 v[204:207], v152 offset:20480
	ds_read_b128 v[208:211], v152 offset:21504
	ds_read_b128 v[212:215], v152 offset:22528
	ds_read_b128 v[216:219], v152 offset:23552
	global_load_lds_dwordx4 v194, s[64:65]
	s_add_i32 m0, s0, 0x2000
	s_add_u32 s0, s64, 0x80000
	s_addc_u32 s1, s65, 0
	s_add_i32 s18, s18, s28
	global_load_lds_dwordx4 v130, s[64:65]
	s_mov_b32 m0, s18
	s_nop 0
	global_load_lds_dwordx4 v194, s[0:1]
	s_add_i32 m0, s18, 0x2000
	s_nop 0
	global_load_lds_dwordx4 v130, s[0:1]
	s_mov_b32 m0, s29
	s_nop 0
	global_load_lds_dwordx4 v194, s[70:71]
	s_mov_b32 m0, s31
	s_nop 0
	global_load_lds_dwordx4 v130, s[70:71]
	s_waitcnt vmcnt(8)
	s_waitcnt lgkmcnt(0)
	s_barrier
	s_setprio 1
	s_waitcnt lgkmcnt(0)
	v_mfma_f32_16x16x32_bf16 v[62:65], v[144:147], v[178:181], v[62:65]
	v_mfma_f32_16x16x32_bf16 v[62:65], v[148:151], v[182:185], v[62:65]
	v_mfma_f32_16x16x32_bf16 v[58:61], v[158:161], v[182:185], v[58:61]
	v_mfma_f32_16x16x32_bf16 v[58:61], v[154:157], v[178:181], v[58:61]
	v_mfma_f32_16x16x32_bf16 v[54:57], v[162:165], v[178:181], v[54:57]
	v_mfma_f32_16x16x32_bf16 v[54:57], v[166:169], v[182:185], v[54:57]
	v_mfma_f32_16x16x32_bf16 v[50:53], v[174:177], v[182:185], v[50:53]
	v_mfma_f32_16x16x32_bf16 v[50:53], v[170:173], v[178:181], v[50:53]
	v_mfma_f32_16x16x32_bf16 v[34:37], v[170:173], v[186:189], v[34:37]
	v_mfma_f32_16x16x32_bf16 v[34:37], v[174:177], v[190:193], v[34:37]
	v_mfma_f32_16x16x32_bf16 v[38:41], v[166:169], v[190:193], v[38:41]
	v_mfma_f32_16x16x32_bf16 v[38:41], v[162:165], v[186:189], v[38:41]
	v_mfma_f32_16x16x32_bf16 v[42:45], v[154:157], v[186:189], v[42:45]
	v_mfma_f32_16x16x32_bf16 v[42:45], v[158:161], v[190:193], v[42:45]
	v_mfma_f32_16x16x32_bf16 v[46:49], v[148:151], v[190:193], v[46:49]
	v_mfma_f32_16x16x32_bf16 v[46:49], v[144:147], v[186:189], v[46:49]
	v_mfma_f32_16x16x32_bf16 v[30:33], v[144:147], v[204:207], v[30:33]
	v_mfma_f32_16x16x32_bf16 v[30:33], v[148:151], v[208:211], v[30:33]
	v_mfma_f32_16x16x32_bf16 v[26:29], v[158:161], v[208:211], v[26:29]
	v_mfma_f32_16x16x32_bf16 v[26:29], v[154:157], v[204:207], v[26:29]
	v_mfma_f32_16x16x32_bf16 v[22:25], v[162:165], v[204:207], v[22:25]
	v_mfma_f32_16x16x32_bf16 v[22:25], v[166:169], v[208:211], v[22:25]
	v_mfma_f32_16x16x32_bf16 v[18:21], v[174:177], v[208:211], v[18:21]
	v_mfma_f32_16x16x32_bf16 v[18:21], v[170:173], v[204:207], v[18:21]
	v_mfma_f32_16x16x32_bf16 v[2:5], v[170:173], v[212:215], v[2:5]
	v_mfma_f32_16x16x32_bf16 v[2:5], v[174:177], v[216:219], v[2:5]
	v_mfma_f32_16x16x32_bf16 v[6:9], v[166:169], v[216:219], v[6:9]
	v_mfma_f32_16x16x32_bf16 v[6:9], v[162:165], v[212:215], v[6:9]
	v_mfma_f32_16x16x32_bf16 v[10:13], v[154:157], v[212:215], v[10:13]
	v_mfma_f32_16x16x32_bf16 v[10:13], v[158:161], v[216:219], v[10:13]
	v_mfma_f32_16x16x32_bf16 v[14:17], v[148:151], v[216:219], v[14:17]
	v_mfma_f32_16x16x32_bf16 v[14:17], v[144:147], v[212:215], v[14:17]
	s_setprio 0
	s_barrier
	s_add_i32 s18, 0, 0x18000
	v_add_u32_e32 v153, s18, v1
	s_add_i32 s19, 0, 0x1c000
	ds_read_b128 v[144:147], v153
	ds_read_b128 v[148:151], v153 offset:1024
	ds_read_b128 v[154:157], v153 offset:2048
	ds_read_b128 v[158:161], v153 offset:3072
	v_add_u32_e32 v153, s19, v1
	ds_read_b128 v[162:165], v153
	ds_read_b128 v[166:169], v153 offset:1024
	ds_read_b128 v[170:173], v153 offset:2048
	ds_read_b128 v[174:177], v153 offset:3072
	s_add_u32 s0, s70, 0x80000
	s_addc_u32 s1, s71, 0
	s_mov_b32 m0, s33
	ds_read_b128 v[178:181], v152 offset:32768
	ds_read_b128 v[182:185], v152 offset:33792
	ds_read_b128 v[186:189], v152 offset:34816
	ds_read_b128 v[190:193], v152 offset:35840
	ds_read_b128 v[204:207], v152 offset:36864
	ds_read_b128 v[208:211], v152 offset:37888
	ds_read_b128 v[212:215], v152 offset:38912
	ds_read_b128 v[216:219], v152 offset:39936
	global_load_lds_dwordx4 v194, s[0:1]
	s_mov_b32 m0, s40
	s_nop 0
	global_load_lds_dwordx4 v130, s[0:1]
	s_waitcnt vmcnt(8)
	s_waitcnt lgkmcnt(0)
	s_barrier
	s_setprio 1
	s_waitcnt lgkmcnt(0)
	v_mfma_f32_16x16x32_bf16 v[126:129], v[144:147], v[178:181], v[126:129]
	v_mfma_f32_16x16x32_bf16 v[126:129], v[148:151], v[182:185], v[126:129]
	v_mfma_f32_16x16x32_bf16 v[122:125], v[158:161], v[182:185], v[122:125]
	v_mfma_f32_16x16x32_bf16 v[122:125], v[154:157], v[178:181], v[122:125]
	v_mfma_f32_16x16x32_bf16 v[118:121], v[162:165], v[178:181], v[118:121]
	v_mfma_f32_16x16x32_bf16 v[118:121], v[166:169], v[182:185], v[118:121]
	v_mfma_f32_16x16x32_bf16 v[114:117], v[174:177], v[182:185], v[114:117]
	v_mfma_f32_16x16x32_bf16 v[114:117], v[170:173], v[178:181], v[114:117]
	v_mfma_f32_16x16x32_bf16 v[98:101], v[170:173], v[186:189], v[98:101]
	v_mfma_f32_16x16x32_bf16 v[98:101], v[174:177], v[190:193], v[98:101]
	v_mfma_f32_16x16x32_bf16 v[102:105], v[166:169], v[190:193], v[102:105]
	v_mfma_f32_16x16x32_bf16 v[102:105], v[162:165], v[186:189], v[102:105]
	v_mfma_f32_16x16x32_bf16 v[106:109], v[154:157], v[186:189], v[106:109]
	v_mfma_f32_16x16x32_bf16 v[106:109], v[158:161], v[190:193], v[106:109]
	v_mfma_f32_16x16x32_bf16 v[110:113], v[148:151], v[190:193], v[110:113]
	v_mfma_f32_16x16x32_bf16 v[110:113], v[144:147], v[186:189], v[110:113]
	v_mfma_f32_16x16x32_bf16 v[94:97], v[144:147], v[204:207], v[94:97]
	v_mfma_f32_16x16x32_bf16 v[94:97], v[148:151], v[208:211], v[94:97]
	v_mfma_f32_16x16x32_bf16 v[90:93], v[158:161], v[208:211], v[90:93]
	v_mfma_f32_16x16x32_bf16 v[90:93], v[154:157], v[204:207], v[90:93]
	v_mfma_f32_16x16x32_bf16 v[86:89], v[162:165], v[204:207], v[86:89]
	v_mfma_f32_16x16x32_bf16 v[86:89], v[166:169], v[208:211], v[86:89]
	v_mfma_f32_16x16x32_bf16 v[82:85], v[174:177], v[208:211], v[82:85]
	v_mfma_f32_16x16x32_bf16 v[82:85], v[170:173], v[204:207], v[82:85]
	v_mfma_f32_16x16x32_bf16 v[66:69], v[170:173], v[212:215], v[66:69]
	v_mfma_f32_16x16x32_bf16 v[66:69], v[174:177], v[216:219], v[66:69]
	v_mfma_f32_16x16x32_bf16 v[70:73], v[166:169], v[216:219], v[70:73]
	v_mfma_f32_16x16x32_bf16 v[70:73], v[162:165], v[212:215], v[70:73]
	v_mfma_f32_16x16x32_bf16 v[74:77], v[154:157], v[212:215], v[74:77]
	v_mfma_f32_16x16x32_bf16 v[74:77], v[158:161], v[216:219], v[74:77]
	v_mfma_f32_16x16x32_bf16 v[78:81], v[148:151], v[216:219], v[78:81]
	v_mfma_f32_16x16x32_bf16 v[78:81], v[144:147], v[212:215], v[78:81]
	s_setprio 0
	s_barrier
	s_add_u32 s98, s64, 0x80
	s_addc_u32 s99, s65, 0
	s_add_u32 s100, s70, 0x80
	s_addc_u32 s101, s71, 0
	s_add_i32 s0, s18, s28
	s_mov_b32 m0, s0
	ds_read_b128 v[178:181], v152 offset:49152
	ds_read_b128 v[182:185], v152 offset:50176
	ds_read_b128 v[186:189], v152 offset:51200
	ds_read_b128 v[190:193], v152 offset:52224
	ds_read_b128 v[204:207], v152 offset:53248
	ds_read_b128 v[208:211], v152 offset:54272
	ds_read_b128 v[212:215], v152 offset:55296
	ds_read_b128 v[216:219], v152 offset:56320
	global_load_lds_dwordx4 v194, s[98:99]
	s_add_i32 m0, s0, 0x2000
	s_add_u32 s0, s64, 0x80080
	s_addc_u32 s1, s65, 0
	s_add_i32 s18, s19, s28
	global_load_lds_dwordx4 v130, s[98:99]
	s_mov_b32 m0, s18
	s_nop 0
	global_load_lds_dwordx4 v194, s[0:1]
	s_add_i32 m0, s18, 0x2000
	s_nop 0
	global_load_lds_dwordx4 v130, s[0:1]
	s_mov_b32 m0, s54
	s_nop 0
	global_load_lds_dwordx4 v194, s[100:101]
	s_mov_b32 m0, s57
	s_nop 0
	global_load_lds_dwordx4 v130, s[100:101]
	s_waitcnt vmcnt(8)
	s_waitcnt lgkmcnt(0)
	s_barrier
	s_setprio 1
	s_waitcnt lgkmcnt(0)
	v_mfma_f32_16x16x32_bf16 v[62:65], v[144:147], v[178:181], v[62:65]
	v_mfma_f32_16x16x32_bf16 v[62:65], v[148:151], v[182:185], v[62:65]
	v_mfma_f32_16x16x32_bf16 v[58:61], v[158:161], v[182:185], v[58:61]
	v_mfma_f32_16x16x32_bf16 v[58:61], v[154:157], v[178:181], v[58:61]
	v_mfma_f32_16x16x32_bf16 v[54:57], v[162:165], v[178:181], v[54:57]
	v_mfma_f32_16x16x32_bf16 v[54:57], v[166:169], v[182:185], v[54:57]
	v_mfma_f32_16x16x32_bf16 v[50:53], v[174:177], v[182:185], v[50:53]
	v_mfma_f32_16x16x32_bf16 v[50:53], v[170:173], v[178:181], v[50:53]
	v_mfma_f32_16x16x32_bf16 v[34:37], v[170:173], v[186:189], v[34:37]
	v_mfma_f32_16x16x32_bf16 v[34:37], v[174:177], v[190:193], v[34:37]
	v_mfma_f32_16x16x32_bf16 v[38:41], v[166:169], v[190:193], v[38:41]
	v_mfma_f32_16x16x32_bf16 v[38:41], v[162:165], v[186:189], v[38:41]
	v_mfma_f32_16x16x32_bf16 v[42:45], v[154:157], v[186:189], v[42:45]
	v_mfma_f32_16x16x32_bf16 v[42:45], v[158:161], v[190:193], v[42:45]
	v_mfma_f32_16x16x32_bf16 v[46:49], v[148:151], v[190:193], v[46:49]
	v_mfma_f32_16x16x32_bf16 v[46:49], v[144:147], v[186:189], v[46:49]
	v_mfma_f32_16x16x32_bf16 v[30:33], v[144:147], v[204:207], v[30:33]
	v_mfma_f32_16x16x32_bf16 v[30:33], v[148:151], v[208:211], v[30:33]
	v_mfma_f32_16x16x32_bf16 v[26:29], v[158:161], v[208:211], v[26:29]
	v_mfma_f32_16x16x32_bf16 v[26:29], v[154:157], v[204:207], v[26:29]
	v_mfma_f32_16x16x32_bf16 v[22:25], v[162:165], v[204:207], v[22:25]
	v_mfma_f32_16x16x32_bf16 v[22:25], v[166:169], v[208:211], v[22:25]
	v_mfma_f32_16x16x32_bf16 v[18:21], v[174:177], v[208:211], v[18:21]
	v_mfma_f32_16x16x32_bf16 v[18:21], v[170:173], v[204:207], v[18:21]
	v_mfma_f32_16x16x32_bf16 v[2:5], v[170:173], v[212:215], v[2:5]
	v_mfma_f32_16x16x32_bf16 v[2:5], v[174:177], v[216:219], v[2:5]
	v_mfma_f32_16x16x32_bf16 v[6:9], v[166:169], v[216:219], v[6:9]
	v_mfma_f32_16x16x32_bf16 v[6:9], v[162:165], v[212:215], v[6:9]
	v_mfma_f32_16x16x32_bf16 v[10:13], v[154:157], v[212:215], v[10:13]
	v_mfma_f32_16x16x32_bf16 v[10:13], v[158:161], v[216:219], v[10:13]
	v_mfma_f32_16x16x32_bf16 v[14:17], v[148:151], v[216:219], v[14:17]
	v_mfma_f32_16x16x32_bf16 v[14:17], v[144:147], v[212:215], v[14:17]
	s_setprio 0
	s_barrier
	s_add_i32 s76, s76, 2
	s_add_u32 s62, s62, 0x100
	s_addc_u32 s63, s63, 0
	s_add_u32 s53, s53, 0x100
	s_addc_u32 s58, s58, 0
	s_cmp_gt_u32 s76, 29
	s_cbranch_scc1 .LBB0_584

.LBB0_645:
	s_add_u32 s64, s8, 0x100
	s_addc_u32 s65, s9, 0
	s_and_b64 s[0:1], s[70:71], exec
	s_cselect_b32 s77, s63, s65
	s_cselect_b32 s76, s62, s64
	s_cselect_b32 s71, s85, s23
	s_cselect_b32 s70, s84, s7
	s_add_i32 s0, 0, 0x10000
	s_add_i32 s18, 0, 0x14000
	v_add_u32_e32 v106, s0, v1
	v_add_u32_e32 v154, s18, v1
	ds_read_b128 v[70:73], v106
	ds_read_b128 v[82:85], v106 offset:1024
	ds_read_b128 v[94:97], v106 offset:2048
	ds_read_b128 v[106:109], v106 offset:3072
	ds_read_b128 v[118:121], v154
	ds_read_b128 v[130:133], v154 offset:1024
	ds_read_b128 v[142:145], v154 offset:2048
	ds_read_b128 v[154:157], v154 offset:3072
	s_add_i32 m0, s29, 0xc000
	ds_read_b128 v[158:161], v237
	ds_read_b128 v[170:173], v237 offset:1024
	ds_read_b128 v[174:177], v237 offset:2048
	ds_read_b128 v[178:181], v237 offset:3072
	ds_read_b128 v[182:185], v237 offset:4096
	ds_read_b128 v[186:189], v237 offset:5120
	ds_read_b128 v[210:213], v237 offset:6144
	ds_read_b128 v[214:217], v237 offset:7168
	global_load_lds_dwordx4 v206, s[8:9]
	s_add_i32 m0, s29, 0xe000
	s_nop 0
	global_load_lds_dwordx4 v208, s[8:9]
	s_waitcnt vmcnt(8)
	s_waitcnt lgkmcnt(0)
	s_barrier
	s_setprio 1
	s_waitcnt lgkmcnt(0)
	v_mfma_f32_16x16x32_bf16 v[166:169], v[70:73], v[158:161], v[166:169]
	v_mfma_f32_16x16x32_bf16 v[166:169], v[82:85], v[170:173], v[166:169]
	v_mfma_f32_16x16x32_bf16 v[162:165], v[106:109], v[170:173], v[162:165]
	v_mfma_f32_16x16x32_bf16 v[162:165], v[94:97], v[158:161], v[162:165]
	v_mfma_f32_16x16x32_bf16 v[150:153], v[118:121], v[158:161], v[150:153]
	v_mfma_f32_16x16x32_bf16 v[150:153], v[130:133], v[170:173], v[150:153]
	v_mfma_f32_16x16x32_bf16 v[146:149], v[154:157], v[170:173], v[146:149]
	v_mfma_f32_16x16x32_bf16 v[146:149], v[142:145], v[158:161], v[146:149]
	v_mfma_f32_16x16x32_bf16 v[122:125], v[142:145], v[174:177], v[122:125]
	v_mfma_f32_16x16x32_bf16 v[122:125], v[154:157], v[178:181], v[122:125]
	v_mfma_f32_16x16x32_bf16 v[126:129], v[130:133], v[178:181], v[126:129]
	v_mfma_f32_16x16x32_bf16 v[126:129], v[118:121], v[174:177], v[126:129]
	v_mfma_f32_16x16x32_bf16 v[134:137], v[94:97], v[174:177], v[134:137]
	v_mfma_f32_16x16x32_bf16 v[134:137], v[106:109], v[178:181], v[134:137]
	v_mfma_f32_16x16x32_bf16 v[138:141], v[82:85], v[178:181], v[138:141]
	v_mfma_f32_16x16x32_bf16 v[138:141], v[70:73], v[174:177], v[138:141]
	v_mfma_f32_16x16x32_bf16 v[114:117], v[70:73], v[182:185], v[114:117]
	v_mfma_f32_16x16x32_bf16 v[114:117], v[82:85], v[186:189], v[114:117]
	v_mfma_f32_16x16x32_bf16 v[110:113], v[106:109], v[186:189], v[110:113]
	v_mfma_f32_16x16x32_bf16 v[110:113], v[94:97], v[182:185], v[110:113]
	v_mfma_f32_16x16x32_bf16 v[102:105], v[118:121], v[182:185], v[102:105]
	v_mfma_f32_16x16x32_bf16 v[102:105], v[130:133], v[186:189], v[102:105]
	v_mfma_f32_16x16x32_bf16 v[98:101], v[154:157], v[186:189], v[98:101]
	v_mfma_f32_16x16x32_bf16 v[98:101], v[142:145], v[182:185], v[98:101]
	v_mfma_f32_16x16x32_bf16 v[74:77], v[142:145], v[210:213], v[74:77]
	v_mfma_f32_16x16x32_bf16 v[74:77], v[154:157], v[214:217], v[74:77]
	v_mfma_f32_16x16x32_bf16 v[78:81], v[130:133], v[214:217], v[78:81]
	v_mfma_f32_16x16x32_bf16 v[78:81], v[118:121], v[210:213], v[78:81]
	v_mfma_f32_16x16x32_bf16 v[86:89], v[94:97], v[210:213], v[86:89]
	v_mfma_f32_16x16x32_bf16 v[86:89], v[106:109], v[214:217], v[86:89]
	v_mfma_f32_16x16x32_bf16 v[90:93], v[82:85], v[214:217], v[90:93]
	v_mfma_f32_16x16x32_bf16 v[90:93], v[70:73], v[210:213], v[90:93]
	s_setprio 0
	s_barrier
	s_add_i32 s0, s0, s28
	s_mov_b32 m0, s0
	ds_read_b128 v[158:161], v237 offset:16384
	ds_read_b128 v[170:173], v237 offset:17408
	ds_read_b128 v[174:177], v237 offset:18432
	ds_read_b128 v[178:181], v237 offset:19456
	ds_read_b128 v[182:185], v237 offset:20480
	ds_read_b128 v[186:189], v237 offset:21504
	ds_read_b128 v[210:213], v237 offset:22528
	ds_read_b128 v[214:217], v237 offset:23552
	global_load_lds_dwordx4 v192, s[70:71]
	s_add_i32 m0, s0, 0x2000
	s_add_u32 s0, s70, 0x160000
	s_addc_u32 s1, s71, 0
	s_add_i32 s8, s18, s28
	global_load_lds_dwordx4 v190, s[70:71]
	s_mov_b32 m0, s8
	s_nop 0
	global_load_lds_dwordx4 v192, s[0:1]
	s_add_i32 m0, s8, 0x2000
	s_nop 0
	global_load_lds_dwordx4 v190, s[0:1]
	s_mov_b32 m0, s29
	s_nop 0
	global_load_lds_dwordx4 v192, s[76:77]
	s_mov_b32 m0, s31
	s_nop 0
	global_load_lds_dwordx4 v190, s[76:77]
	s_waitcnt vmcnt(8)
	s_waitcnt lgkmcnt(0)
	s_barrier
	s_setprio 1
	s_waitcnt lgkmcnt(0)
	v_mfma_f32_16x16x32_bf16 v[62:65], v[70:73], v[158:161], v[62:65]
	v_mfma_f32_16x16x32_bf16 v[62:65], v[82:85], v[170:173], v[62:65]
	v_mfma_f32_16x16x32_bf16 v[58:61], v[106:109], v[170:173], v[58:61]
	v_mfma_f32_16x16x32_bf16 v[58:61], v[94:97], v[158:161], v[58:61]
	v_mfma_f32_16x16x32_bf16 v[54:57], v[118:121], v[158:161], v[54:57]
	v_mfma_f32_16x16x32_bf16 v[54:57], v[130:133], v[170:173], v[54:57]
	v_mfma_f32_16x16x32_bf16 v[50:53], v[154:157], v[170:173], v[50:53]
	v_mfma_f32_16x16x32_bf16 v[50:53], v[142:145], v[158:161], v[50:53]
	v_mfma_f32_16x16x32_bf16 v[34:37], v[142:145], v[174:177], v[34:37]
	v_mfma_f32_16x16x32_bf16 v[34:37], v[154:157], v[178:181], v[34:37]
	v_mfma_f32_16x16x32_bf16 v[38:41], v[130:133], v[178:181], v[38:41]
	v_mfma_f32_16x16x32_bf16 v[38:41], v[118:121], v[174:177], v[38:41]
	v_mfma_f32_16x16x32_bf16 v[42:45], v[94:97], v[174:177], v[42:45]
	v_mfma_f32_16x16x32_bf16 v[42:45], v[106:109], v[178:181], v[42:45]
	v_mfma_f32_16x16x32_bf16 v[46:49], v[82:85], v[178:181], v[46:49]
	v_mfma_f32_16x16x32_bf16 v[46:49], v[70:73], v[174:177], v[46:49]
	v_mfma_f32_16x16x32_bf16 v[30:33], v[70:73], v[182:185], v[30:33]
	v_mfma_f32_16x16x32_bf16 v[30:33], v[82:85], v[186:189], v[30:33]
	v_mfma_f32_16x16x32_bf16 v[26:29], v[106:109], v[186:189], v[26:29]
	v_mfma_f32_16x16x32_bf16 v[26:29], v[94:97], v[182:185], v[26:29]
	v_mfma_f32_16x16x32_bf16 v[22:25], v[118:121], v[182:185], v[22:25]
	v_mfma_f32_16x16x32_bf16 v[22:25], v[130:133], v[186:189], v[22:25]
	v_mfma_f32_16x16x32_bf16 v[18:21], v[154:157], v[186:189], v[18:21]
	v_mfma_f32_16x16x32_bf16 v[18:21], v[142:145], v[182:185], v[18:21]
	v_mfma_f32_16x16x32_bf16 v[2:5], v[142:145], v[210:213], v[2:5]
	v_mfma_f32_16x16x32_bf16 v[2:5], v[154:157], v[214:217], v[2:5]
	v_mfma_f32_16x16x32_bf16 v[6:9], v[130:133], v[214:217], v[6:9]
	v_mfma_f32_16x16x32_bf16 v[6:9], v[118:121], v[210:213], v[6:9]
	v_mfma_f32_16x16x32_bf16 v[10:13], v[94:97], v[210:213], v[10:13]
	v_mfma_f32_16x16x32_bf16 v[10:13], v[106:109], v[214:217], v[10:13]
	v_mfma_f32_16x16x32_bf16 v[14:17], v[82:85], v[214:217], v[14:17]
	v_mfma_f32_16x16x32_bf16 v[14:17], v[70:73], v[210:213], v[14:17]
	s_setprio 0
	s_barrier
	s_add_i32 s8, 0, 0x18000
	s_add_i32 s9, 0, 0x1c000
	v_add_u32_e32 v106, s8, v1
	v_add_u32_e32 v154, s9, v1
	ds_read_b128 v[70:73], v106
	ds_read_b128 v[82:85], v106 offset:1024
	ds_read_b128 v[94:97], v106 offset:2048
	ds_read_b128 v[106:109], v106 offset:3072
	ds_read_b128 v[118:121], v154
	ds_read_b128 v[130:133], v154 offset:1024
	ds_read_b128 v[142:145], v154 offset:2048
	ds_read_b128 v[154:157], v154 offset:3072
	s_add_u32 s0, s76, 0x160000
	s_addc_u32 s1, s77, 0
	s_mov_b32 m0, s33
	ds_read_b128 v[158:161], v237 offset:32768
	ds_read_b128 v[170:173], v237 offset:33792
	ds_read_b128 v[174:177], v237 offset:34816
	ds_read_b128 v[178:181], v237 offset:35840
	ds_read_b128 v[182:185], v237 offset:36864
	ds_read_b128 v[186:189], v237 offset:37888
	ds_read_b128 v[210:213], v237 offset:38912
	ds_read_b128 v[214:217], v237 offset:39936
	global_load_lds_dwordx4 v192, s[0:1]
	s_mov_b32 m0, s43
	s_nop 0
	global_load_lds_dwordx4 v190, s[0:1]
	s_waitcnt vmcnt(8)
	s_waitcnt lgkmcnt(0)
	s_barrier
	s_setprio 1
	s_waitcnt lgkmcnt(0)
	v_mfma_f32_16x16x32_bf16 v[166:169], v[70:73], v[158:161], v[166:169]
	v_mfma_f32_16x16x32_bf16 v[166:169], v[82:85], v[170:173], v[166:169]
	v_mfma_f32_16x16x32_bf16 v[162:165], v[106:109], v[170:173], v[162:165]
	v_mfma_f32_16x16x32_bf16 v[162:165], v[94:97], v[158:161], v[162:165]
	v_mfma_f32_16x16x32_bf16 v[150:153], v[118:121], v[158:161], v[150:153]
	v_mfma_f32_16x16x32_bf16 v[150:153], v[130:133], v[170:173], v[150:153]
	v_mfma_f32_16x16x32_bf16 v[146:149], v[154:157], v[170:173], v[146:149]
	v_mfma_f32_16x16x32_bf16 v[146:149], v[142:145], v[158:161], v[146:149]
	v_mfma_f32_16x16x32_bf16 v[122:125], v[142:145], v[174:177], v[122:125]
	v_mfma_f32_16x16x32_bf16 v[122:125], v[154:157], v[178:181], v[122:125]
	v_mfma_f32_16x16x32_bf16 v[126:129], v[130:133], v[178:181], v[126:129]
	v_mfma_f32_16x16x32_bf16 v[126:129], v[118:121], v[174:177], v[126:129]
	v_mfma_f32_16x16x32_bf16 v[134:137], v[94:97], v[174:177], v[134:137]
	v_mfma_f32_16x16x32_bf16 v[134:137], v[106:109], v[178:181], v[134:137]
	v_mfma_f32_16x16x32_bf16 v[138:141], v[82:85], v[178:181], v[138:141]
	v_mfma_f32_16x16x32_bf16 v[138:141], v[70:73], v[174:177], v[138:141]
	v_mfma_f32_16x16x32_bf16 v[114:117], v[70:73], v[182:185], v[114:117]
	v_mfma_f32_16x16x32_bf16 v[114:117], v[82:85], v[186:189], v[114:117]
	v_mfma_f32_16x16x32_bf16 v[110:113], v[106:109], v[186:189], v[110:113]
	v_mfma_f32_16x16x32_bf16 v[110:113], v[94:97], v[182:185], v[110:113]
	v_mfma_f32_16x16x32_bf16 v[102:105], v[118:121], v[182:185], v[102:105]
	v_mfma_f32_16x16x32_bf16 v[102:105], v[130:133], v[186:189], v[102:105]
	v_mfma_f32_16x16x32_bf16 v[98:101], v[154:157], v[186:189], v[98:101]
	v_mfma_f32_16x16x32_bf16 v[98:101], v[142:145], v[182:185], v[98:101]
	v_mfma_f32_16x16x32_bf16 v[74:77], v[142:145], v[210:213], v[74:77]
	v_mfma_f32_16x16x32_bf16 v[74:77], v[154:157], v[214:217], v[74:77]
	v_mfma_f32_16x16x32_bf16 v[78:81], v[130:133], v[214:217], v[78:81]
	v_mfma_f32_16x16x32_bf16 v[78:81], v[118:121], v[210:213], v[78:81]
	v_mfma_f32_16x16x32_bf16 v[86:89], v[94:97], v[210:213], v[86:89]
	v_mfma_f32_16x16x32_bf16 v[86:89], v[106:109], v[214:217], v[86:89]
	v_mfma_f32_16x16x32_bf16 v[90:93], v[82:85], v[214:217], v[90:93]
	v_mfma_f32_16x16x32_bf16 v[90:93], v[70:73], v[210:213], v[90:93]
	s_setprio 0
	s_barrier
	s_add_u32 s98, s70, 0x80
	s_addc_u32 s99, s71, 0
	s_add_u32 s100, s76, 0x80
	s_addc_u32 s101, s77, 0
	s_add_i32 s0, s8, s28
	s_mov_b32 m0, s0
	ds_read_b128 v[158:161], v237 offset:49152
	ds_read_b128 v[170:173], v237 offset:50176
	ds_read_b128 v[174:177], v237 offset:51200
	ds_read_b128 v[178:181], v237 offset:52224
	ds_read_b128 v[182:185], v237 offset:53248
	ds_read_b128 v[186:189], v237 offset:54272
	ds_read_b128 v[210:213], v237 offset:55296
	ds_read_b128 v[214:217], v237 offset:56320
	global_load_lds_dwordx4 v192, s[98:99]
	s_add_i32 m0, s0, 0x2000
	s_add_u32 s0, s70, 0x160080
	s_addc_u32 s1, s71, 0
	s_add_i32 s8, s9, s28
	global_load_lds_dwordx4 v190, s[98:99]
	s_mov_b32 m0, s8
	s_nop 0
	global_load_lds_dwordx4 v192, s[0:1]
	s_add_i32 m0, s8, 0x2000
	s_nop 0
	global_load_lds_dwordx4 v190, s[0:1]
	s_mov_b32 m0, s68
	s_nop 0
	global_load_lds_dwordx4 v192, s[100:101]
	s_mov_b32 m0, s79
	s_nop 0
	global_load_lds_dwordx4 v190, s[100:101]
	s_waitcnt vmcnt(8)
	s_waitcnt lgkmcnt(0)
	s_barrier
	s_setprio 1
	s_waitcnt lgkmcnt(0)
	v_mfma_f32_16x16x32_bf16 v[62:65], v[70:73], v[158:161], v[62:65]
	v_mfma_f32_16x16x32_bf16 v[62:65], v[82:85], v[170:173], v[62:65]
	v_mfma_f32_16x16x32_bf16 v[58:61], v[106:109], v[170:173], v[58:61]
	v_mfma_f32_16x16x32_bf16 v[58:61], v[94:97], v[158:161], v[58:61]
	v_mfma_f32_16x16x32_bf16 v[54:57], v[118:121], v[158:161], v[54:57]
	v_mfma_f32_16x16x32_bf16 v[54:57], v[130:133], v[170:173], v[54:57]
	v_mfma_f32_16x16x32_bf16 v[50:53], v[154:157], v[170:173], v[50:53]
	v_mfma_f32_16x16x32_bf16 v[50:53], v[142:145], v[158:161], v[50:53]
	v_mfma_f32_16x16x32_bf16 v[34:37], v[142:145], v[174:177], v[34:37]
	v_mfma_f32_16x16x32_bf16 v[34:37], v[154:157], v[178:181], v[34:37]
	v_mfma_f32_16x16x32_bf16 v[38:41], v[130:133], v[178:181], v[38:41]
	v_mfma_f32_16x16x32_bf16 v[38:41], v[118:121], v[174:177], v[38:41]
	v_mfma_f32_16x16x32_bf16 v[42:45], v[94:97], v[174:177], v[42:45]
	v_mfma_f32_16x16x32_bf16 v[42:45], v[106:109], v[178:181], v[42:45]
	v_mfma_f32_16x16x32_bf16 v[46:49], v[82:85], v[178:181], v[46:49]
	v_mfma_f32_16x16x32_bf16 v[46:49], v[70:73], v[174:177], v[46:49]
	v_mfma_f32_16x16x32_bf16 v[30:33], v[70:73], v[182:185], v[30:33]
	v_mfma_f32_16x16x32_bf16 v[30:33], v[82:85], v[186:189], v[30:33]
	v_mfma_f32_16x16x32_bf16 v[26:29], v[106:109], v[186:189], v[26:29]
	v_mfma_f32_16x16x32_bf16 v[26:29], v[94:97], v[182:185], v[26:29]
	v_mfma_f32_16x16x32_bf16 v[22:25], v[118:121], v[182:185], v[22:25]
	v_mfma_f32_16x16x32_bf16 v[22:25], v[130:133], v[186:189], v[22:25]
	v_mfma_f32_16x16x32_bf16 v[18:21], v[154:157], v[186:189], v[18:21]
	v_mfma_f32_16x16x32_bf16 v[18:21], v[142:145], v[182:185], v[18:21]
	v_mfma_f32_16x16x32_bf16 v[2:5], v[142:145], v[210:213], v[2:5]
	v_mfma_f32_16x16x32_bf16 v[2:5], v[154:157], v[214:217], v[2:5]
	v_mfma_f32_16x16x32_bf16 v[6:9], v[130:133], v[214:217], v[6:9]
	v_mfma_f32_16x16x32_bf16 v[6:9], v[118:121], v[210:213], v[6:9]
	v_mfma_f32_16x16x32_bf16 v[10:13], v[94:97], v[210:213], v[10:13]
	v_mfma_f32_16x16x32_bf16 v[10:13], v[106:109], v[214:217], v[10:13]
	v_mfma_f32_16x16x32_bf16 v[14:17], v[82:85], v[214:217], v[14:17]
	v_mfma_f32_16x16x32_bf16 v[14:17], v[70:73], v[210:213], v[14:17]
	s_setprio 0
	s_barrier
	s_add_i32 s41, s41, 2
	s_add_u32 s7, s7, 0x100
	s_addc_u32 s23, s23, 0
	s_cmpk_gt_u32 s41, 0x55
	s_mov_b64 s[8:9], s[64:65]
	s_cbranch_scc1 .LBB0_648

	.amdhsa_kernel _Z8mega_fwd4Args
		.amdhsa_group_segment_fixed_size 0
		.amdhsa_private_segment_fixed_size 0
		.amdhsa_kernarg_size 432
		.amdhsa_user_sgpr_count 2
		.amdhsa_user_sgpr_dispatch_ptr 0
		.amdhsa_user_sgpr_queue_ptr 0
		.amdhsa_user_sgpr_kernarg_segment_ptr 1
		.amdhsa_user_sgpr_dispatch_id 0
		.amdhsa_user_sgpr_kernarg_preload_length 0
		.amdhsa_user_sgpr_kernarg_preload_offset 0
		.amdhsa_user_sgpr_private_segment_size 0
		.amdhsa_uses_dynamic_stack 0
		.amdhsa_enable_private_segment 0
		.amdhsa_system_sgpr_workgroup_id_x 1
		.amdhsa_system_sgpr_workgroup_id_y 0
		.amdhsa_system_sgpr_workgroup_id_z 0
		.amdhsa_system_sgpr_workgroup_info 0
		.amdhsa_system_vgpr_workitem_id 0
		.amdhsa_next_free_vgpr 256
		.amdhsa_next_free_sgpr 102
		.amdhsa_accum_offset 256
		.amdhsa_reserve_vcc 1
		.amdhsa_float_round_mode_32 0
		.amdhsa_float_round_mode_16_64 0
		.amdhsa_float_denorm_mode_32 3
		.amdhsa_float_denorm_mode_16_64 3
		.amdhsa_dx10_clamp 1
		.amdhsa_ieee_mode 1
		.amdhsa_fp16_overflow 0
		.amdhsa_tg_split 0
		.amdhsa_exception_fp_ieee_invalid_op 0
		.amdhsa_exception_fp_denorm_src 0
		.amdhsa_exception_fp_ieee_div_zero 0
		.amdhsa_exception_fp_ieee_overflow 0
		.amdhsa_exception_fp_ieee_underflow 0
		.amdhsa_exception_fp_ieee_inexact 0
		.amdhsa_exception_int_div_zero 0
	.end_amdhsa_kernel

amdhsa.kernels:
  - .agpr_count:     0
    .args:
      - .offset:         0
        .size:           176
        .value_kind:     by_value
      - .offset:         176
        .size:           4
        .value_kind:     hidden_block_count_x
      - .offset:         180
        .size:           4
        .value_kind:     hidden_block_count_y
      - .offset:         184
        .size:           4
        .value_kind:     hidden_block_count_z
      - .offset:         188
        .size:           2
        .value_kind:     hidden_group_size_x
      - .offset:         190
        .size:           2
        .value_kind:     hidden_group_size_y
      - .offset:         192
        .size:           2
        .value_kind:     hidden_group_size_z
      - .offset:         194
        .size:           2
        .value_kind:     hidden_remainder_x
      - .offset:         196
        .size:           2
        .value_kind:     hidden_remainder_y
      - .offset:         198
        .size:           2
        .value_kind:     hidden_remainder_z
      - .offset:         216
        .size:           8
        .value_kind:     hidden_global_offset_x
      - .offset:         224
        .size:           8
        .value_kind:     hidden_global_offset_y
      - .offset:         232
        .size:           8
        .value_kind:     hidden_global_offset_z
      - .offset:         240
        .size:           2
        .value_kind:     hidden_grid_dims
      - .offset:         296
        .size:           4
        .value_kind:     hidden_dynamic_lds_size
    .group_segment_fixed_size: 0
    .kernarg_segment_align: 8
    .kernarg_segment_size: 432
    .language:       OpenCL C
    .language_version:
      - 2
      - 0
    .max_flat_workgroup_size: 512
    .name:           _Z8mega_fwd4Args
    .private_segment_fixed_size: 0
    .sgpr_count:     108
    .sgpr_spill_count: 111
    .symbol:         _Z8mega_fwd4Args.kd
    .uniform_work_group_size: 1
    .uses_dynamic_stack: false
    .vgpr_count:     256
    .vgpr_spill_count: 0
    .wavefront_size: 64
